# GEMM loops: removed the duplicate lgkmcnt(0) behind each pre-MFMA wait (24 sites), on top of BCEG
# speedup vs baseline: 1.0016x; 1.0016x over previous
.LBB0_197:
	ds_read_b128 v[144:147], v151
	ds_read_b128 v[154:157], v151 offset:1024
	ds_read_b128 v[158:161], v151 offset:2048
	ds_read_b128 v[162:165], v151 offset:3072
	s_add_u32 s18, s16, 0xfff80080
	s_addc_u32 s19, s17, -1
	s_cmp_eq_u32 s78, 28
	s_cselect_b32 s21, s5, s19
	s_cselect_b32 s20, s9, s18
	s_cselect_b32 s19, s7, s77
	s_cselect_b32 s18, s15, s76
	v_lshl_add_u64 v[198:199], s[16:17], 0, v[136:137]
	s_add_i32 m0, s24, 0xc000
	ds_read_b128 v[166:169], v152
	ds_read_b128 v[170:173], v152 offset:1024
	ds_read_b128 v[174:177], v152 offset:2048
	ds_read_b128 v[178:181], v152 offset:3072
	ds_read_b128 v[182:185], v152 offset:4096
	ds_read_b128 v[186:189], v152 offset:5120
	ds_read_b128 v[190:193], v152 offset:6144
	ds_read_b128 v[194:197], v152 offset:7168
	global_load_lds_dwordx4 v[198:199], off
	v_lshl_add_u64 v[198:199], s[16:17], 0, v[138:139]
	s_add_i32 m0, s24, 0xe000
	s_nop 0
	global_load_lds_dwordx4 v[198:199], off
	s_waitcnt lgkmcnt(8)
	s_barrier
	s_waitcnt lgkmcnt(0)
	s_setprio 1
	v_mfma_f32_16x16x32_f16 v[124:127], v[144:147], v[166:169], v[124:127]
	v_mfma_f32_16x16x32_f16 v[120:123], v[158:161], v[166:169], v[120:123]
	v_mfma_f32_16x16x32_f16 v[108:111], v[144:147], v[174:177], v[108:111]
	v_mfma_f32_16x16x32_f16 v[104:107], v[158:161], v[174:177], v[104:107]
	v_mfma_f32_16x16x32_f16 v[92:95], v[144:147], v[182:185], v[92:95]
	v_mfma_f32_16x16x32_f16 v[88:91], v[158:161], v[182:185], v[88:91]
	v_mfma_f32_16x16x32_f16 v[76:79], v[144:147], v[190:193], v[76:79]
	v_mfma_f32_16x16x32_f16 v[72:75], v[158:161], v[190:193], v[72:75]
	v_mfma_f32_16x16x32_f16 v[124:127], v[154:157], v[170:173], v[124:127]
	v_mfma_f32_16x16x32_f16 v[120:123], v[162:165], v[170:173], v[120:123]
	v_mfma_f32_16x16x32_f16 v[108:111], v[154:157], v[178:181], v[108:111]
	v_mfma_f32_16x16x32_f16 v[104:107], v[162:165], v[178:181], v[104:107]
	v_mfma_f32_16x16x32_f16 v[92:95], v[154:157], v[186:189], v[92:95]
	v_mfma_f32_16x16x32_f16 v[88:91], v[162:165], v[186:189], v[88:91]
	v_mfma_f32_16x16x32_f16 v[76:79], v[154:157], v[194:197], v[76:79]
	v_mfma_f32_16x16x32_f16 v[72:75], v[162:165], v[194:197], v[72:75]
	s_setprio 0
	s_barrier
	s_add_i32 s79, s68, s23
	v_lshl_add_u64 v[214:215], s[18:19], 0, v[130:131]
	s_mov_b32 m0, s79
	ds_read_b128 v[198:201], v153
	ds_read_b128 v[202:205], v153 offset:1024
	ds_read_b128 v[206:209], v153 offset:2048
	ds_read_b128 v[210:213], v153 offset:3072
	global_load_lds_dwordx4 v[214:215], off
	v_lshl_add_u64 v[216:217], s[18:19], 0, v[134:135]
	s_add_i32 m0, s79, 0x2000
	s_nop 0
	global_load_lds_dwordx4 v[216:217], off
	s_barrier
	s_waitcnt lgkmcnt(0)
	s_setprio 1
	v_mfma_f32_16x16x32_f16 v[116:119], v[198:201], v[166:169], v[116:119]
	v_mfma_f32_16x16x32_f16 v[112:115], v[206:209], v[166:169], v[112:115]
	v_mfma_f32_16x16x32_f16 v[100:103], v[198:201], v[174:177], v[100:103]
	v_mfma_f32_16x16x32_f16 v[96:99], v[206:209], v[174:177], v[96:99]
	v_mfma_f32_16x16x32_f16 v[84:87], v[198:201], v[182:185], v[84:87]
	v_mfma_f32_16x16x32_f16 v[80:83], v[206:209], v[182:185], v[80:83]
	v_mfma_f32_16x16x32_f16 v[68:71], v[198:201], v[190:193], v[68:71]
	v_mfma_f32_16x16x32_f16 v[64:67], v[206:209], v[190:193], v[64:67]
	v_mfma_f32_16x16x32_f16 v[116:119], v[202:205], v[170:173], v[116:119]
	v_mfma_f32_16x16x32_f16 v[112:115], v[210:213], v[170:173], v[112:115]
	v_mfma_f32_16x16x32_f16 v[100:103], v[202:205], v[178:181], v[100:103]
	v_mfma_f32_16x16x32_f16 v[96:99], v[210:213], v[178:181], v[96:99]
	v_mfma_f32_16x16x32_f16 v[84:87], v[202:205], v[186:189], v[84:87]
	v_mfma_f32_16x16x32_f16 v[80:83], v[210:213], v[186:189], v[80:83]
	v_mfma_f32_16x16x32_f16 v[68:71], v[202:205], v[194:197], v[68:71]
	v_mfma_f32_16x16x32_f16 v[64:67], v[210:213], v[194:197], v[64:67]
	s_setprio 0
	s_mov_b32 m0, s24
	v_lshl_add_u64 v[218:219], s[20:21], 0, v[128:129]
	s_barrier
	ds_read_b128 v[166:169], v152 offset:16384
	ds_read_b128 v[170:173], v152 offset:17408
	ds_read_b128 v[174:177], v152 offset:18432
	ds_read_b128 v[178:181], v152 offset:19456
	ds_read_b128 v[182:185], v152 offset:20480
	ds_read_b128 v[186:189], v152 offset:21504
	ds_read_b128 v[190:193], v152 offset:22528
	ds_read_b128 v[194:197], v152 offset:23552
	global_load_lds_dwordx4 v[218:219], off
	v_lshl_add_u64 v[220:221], s[20:21], 0, v[132:133]
	s_mov_b32 m0, s25
	s_nop 0
	global_load_lds_dwordx4 v[220:221], off
	s_barrier
	s_waitcnt lgkmcnt(0)
	s_setprio 1
	v_mfma_f32_16x16x32_f16 v[60:63], v[144:147], v[166:169], v[60:63]
	v_mfma_f32_16x16x32_f16 v[56:59], v[158:161], v[166:169], v[56:59]
	v_mfma_f32_16x16x32_f16 v[44:47], v[144:147], v[174:177], v[44:47]
	v_mfma_f32_16x16x32_f16 v[40:43], v[158:161], v[174:177], v[40:43]
	v_mfma_f32_16x16x32_f16 v[28:31], v[144:147], v[182:185], v[28:31]
	v_mfma_f32_16x16x32_f16 v[24:27], v[158:161], v[182:185], v[24:27]
	v_mfma_f32_16x16x32_f16 v[12:15], v[144:147], v[190:193], v[12:15]
	v_mfma_f32_16x16x32_f16 v[8:11], v[158:161], v[190:193], v[8:11]
	v_mfma_f32_16x16x32_f16 v[60:63], v[154:157], v[170:173], v[60:63]
	v_mfma_f32_16x16x32_f16 v[56:59], v[162:165], v[170:173], v[56:59]
	v_mfma_f32_16x16x32_f16 v[44:47], v[154:157], v[178:181], v[44:47]
	v_mfma_f32_16x16x32_f16 v[40:43], v[162:165], v[178:181], v[40:43]
	v_mfma_f32_16x16x32_f16 v[28:31], v[154:157], v[186:189], v[28:31]
	v_mfma_f32_16x16x32_f16 v[24:27], v[162:165], v[186:189], v[24:27]
	v_mfma_f32_16x16x32_f16 v[12:15], v[154:157], v[194:197], v[12:15]
	v_mfma_f32_16x16x32_f16 v[8:11], v[162:165], v[194:197], v[8:11]
	s_setprio 0
	s_barrier
	s_add_u32 s80, s18, 0x80000
	s_addc_u32 s81, s19, 0
	s_add_i32 s79, s69, s23
	v_lshl_add_u64 v[144:145], s[80:81], 0, v[130:131]
	s_mov_b32 m0, s79
	s_nop 0
	global_load_lds_dwordx4 v[144:145], off
	v_lshl_add_u64 v[144:145], s[80:81], 0, v[134:135]
	s_add_i32 m0, s79, 0x2000
	s_nop 0
	global_load_lds_dwordx4 v[144:145], off
	s_waitcnt vmcnt(6)
	s_barrier
	s_setprio 1
	v_mfma_f32_16x16x32_f16 v[52:55], v[198:201], v[166:169], v[52:55]
	v_mfma_f32_16x16x32_f16 v[48:51], v[206:209], v[166:169], v[48:51]
	v_mfma_f32_16x16x32_f16 v[36:39], v[198:201], v[174:177], v[36:39]
	v_mfma_f32_16x16x32_f16 v[32:35], v[206:209], v[174:177], v[32:35]
	v_mfma_f32_16x16x32_f16 v[20:23], v[198:201], v[182:185], v[20:23]
	v_mfma_f32_16x16x32_f16 v[16:19], v[206:209], v[182:185], v[16:19]
	v_mfma_f32_16x16x32_f16 v[4:7], v[198:201], v[190:193], v[4:7]
	v_mfma_f32_16x16x32_f16 v[0:3], v[206:209], v[190:193], v[0:3]
	v_mfma_f32_16x16x32_f16 v[52:55], v[202:205], v[170:173], v[52:55]
	v_mfma_f32_16x16x32_f16 v[48:51], v[210:213], v[170:173], v[48:51]
	v_mfma_f32_16x16x32_f16 v[36:39], v[202:205], v[178:181], v[36:39]
	v_mfma_f32_16x16x32_f16 v[32:35], v[210:213], v[178:181], v[32:35]
	v_mfma_f32_16x16x32_f16 v[20:23], v[202:205], v[186:189], v[20:23]
	v_mfma_f32_16x16x32_f16 v[16:19], v[210:213], v[186:189], v[16:19]
	v_mfma_f32_16x16x32_f16 v[4:7], v[202:205], v[194:197], v[4:7]
	v_mfma_f32_16x16x32_f16 v[0:3], v[210:213], v[194:197], v[0:3]
	s_setprio 0
	s_add_i32 s79, 0, 0x18000
	v_add_u32_e32 v162, s79, v149
	s_barrier
	ds_read_b128 v[144:147], v162
	ds_read_b128 v[154:157], v162 offset:1024
	ds_read_b128 v[158:161], v162 offset:2048
	ds_read_b128 v[162:165], v162 offset:3072
	s_add_u32 s20, s20, 0x80000
	s_addc_u32 s21, s21, 0
	s_mov_b32 m0, s26
	v_lshl_add_u64 v[198:199], s[20:21], 0, v[128:129]
	ds_read_b128 v[166:169], v152 offset:32768
	ds_read_b128 v[170:173], v152 offset:33792
	ds_read_b128 v[174:177], v152 offset:34816
	ds_read_b128 v[178:181], v152 offset:35840
	ds_read_b128 v[182:185], v152 offset:36864
	ds_read_b128 v[186:189], v152 offset:37888
	ds_read_b128 v[190:193], v152 offset:38912
	ds_read_b128 v[194:197], v152 offset:39936
	global_load_lds_dwordx4 v[198:199], off
	v_lshl_add_u64 v[198:199], s[20:21], 0, v[132:133]
	s_mov_b32 m0, s27
	s_nop 0
	global_load_lds_dwordx4 v[198:199], off
	s_waitcnt lgkmcnt(8)
	s_barrier
	s_waitcnt lgkmcnt(0)
	s_setprio 1
	v_mfma_f32_16x16x32_f16 v[124:127], v[144:147], v[166:169], v[124:127]
	v_mfma_f32_16x16x32_f16 v[120:123], v[158:161], v[166:169], v[120:123]
	v_mfma_f32_16x16x32_f16 v[108:111], v[144:147], v[174:177], v[108:111]
	v_mfma_f32_16x16x32_f16 v[104:107], v[158:161], v[174:177], v[104:107]
	v_mfma_f32_16x16x32_f16 v[92:95], v[144:147], v[182:185], v[92:95]
	v_mfma_f32_16x16x32_f16 v[88:91], v[158:161], v[182:185], v[88:91]
	v_mfma_f32_16x16x32_f16 v[76:79], v[144:147], v[190:193], v[76:79]
	v_mfma_f32_16x16x32_f16 v[72:75], v[158:161], v[190:193], v[72:75]
	v_mfma_f32_16x16x32_f16 v[124:127], v[154:157], v[170:173], v[124:127]
	v_mfma_f32_16x16x32_f16 v[120:123], v[162:165], v[170:173], v[120:123]
	v_mfma_f32_16x16x32_f16 v[108:111], v[154:157], v[178:181], v[108:111]
	v_mfma_f32_16x16x32_f16 v[104:107], v[162:165], v[178:181], v[104:107]
	v_mfma_f32_16x16x32_f16 v[92:95], v[154:157], v[186:189], v[92:95]
	v_mfma_f32_16x16x32_f16 v[88:91], v[162:165], v[186:189], v[88:91]
	v_mfma_f32_16x16x32_f16 v[76:79], v[154:157], v[194:197], v[76:79]
	v_mfma_f32_16x16x32_f16 v[72:75], v[162:165], v[194:197], v[72:75]
	s_setprio 0
	s_barrier
	s_add_i32 s20, 0, 0x1c000
	s_add_i32 s21, s79, s23
	v_add_u32_e32 v210, s20, v149
	v_lshl_add_u64 v[214:215], v[214:215], 0, s[0:1]
	s_mov_b32 m0, s21
	ds_read_b128 v[198:201], v210
	ds_read_b128 v[202:205], v210 offset:1024
	ds_read_b128 v[206:209], v210 offset:2048
	ds_read_b128 v[210:213], v210 offset:3072
	global_load_lds_dwordx4 v[214:215], off
	v_lshl_add_u64 v[214:215], v[216:217], 0, s[0:1]
	s_add_i32 m0, s21, 0x2000
	s_nop 0
	global_load_lds_dwordx4 v[214:215], off
	s_barrier
	s_waitcnt lgkmcnt(0)
	s_setprio 1
	v_mfma_f32_16x16x32_f16 v[116:119], v[198:201], v[166:169], v[116:119]
	v_mfma_f32_16x16x32_f16 v[112:115], v[206:209], v[166:169], v[112:115]
	v_mfma_f32_16x16x32_f16 v[100:103], v[198:201], v[174:177], v[100:103]
	v_mfma_f32_16x16x32_f16 v[96:99], v[206:209], v[174:177], v[96:99]
	v_mfma_f32_16x16x32_f16 v[84:87], v[198:201], v[182:185], v[84:87]
	v_mfma_f32_16x16x32_f16 v[80:83], v[206:209], v[182:185], v[80:83]
	v_mfma_f32_16x16x32_f16 v[68:71], v[198:201], v[190:193], v[68:71]
	v_mfma_f32_16x16x32_f16 v[64:67], v[206:209], v[190:193], v[64:67]
	v_mfma_f32_16x16x32_f16 v[116:119], v[202:205], v[170:173], v[116:119]
	v_mfma_f32_16x16x32_f16 v[112:115], v[210:213], v[170:173], v[112:115]
	v_mfma_f32_16x16x32_f16 v[100:103], v[202:205], v[178:181], v[100:103]
	v_mfma_f32_16x16x32_f16 v[96:99], v[210:213], v[178:181], v[96:99]
	v_mfma_f32_16x16x32_f16 v[84:87], v[202:205], v[186:189], v[84:87]
	v_mfma_f32_16x16x32_f16 v[80:83], v[210:213], v[186:189], v[80:83]
	v_mfma_f32_16x16x32_f16 v[68:71], v[202:205], v[194:197], v[68:71]
	v_mfma_f32_16x16x32_f16 v[64:67], v[210:213], v[194:197], v[64:67]
	s_setprio 0
	s_mov_b32 m0, s29
	v_lshl_add_u64 v[214:215], v[218:219], 0, s[0:1]
	s_barrier
	ds_read_b128 v[166:169], v152 offset:49152
	ds_read_b128 v[170:173], v152 offset:50176
	ds_read_b128 v[174:177], v152 offset:51200
	ds_read_b128 v[178:181], v152 offset:52224
	ds_read_b128 v[182:185], v152 offset:53248
	ds_read_b128 v[186:189], v152 offset:54272
	ds_read_b128 v[190:193], v152 offset:55296
	ds_read_b128 v[194:197], v152 offset:56320
	global_load_lds_dwordx4 v[214:215], off
	v_lshl_add_u64 v[214:215], v[220:221], 0, s[0:1]
	s_mov_b32 m0, s30
	s_nop 0
	global_load_lds_dwordx4 v[214:215], off
	s_barrier
	s_waitcnt lgkmcnt(0)
	s_setprio 1
	v_mfma_f32_16x16x32_f16 v[60:63], v[144:147], v[166:169], v[60:63]
	v_mfma_f32_16x16x32_f16 v[56:59], v[158:161], v[166:169], v[56:59]
	v_mfma_f32_16x16x32_f16 v[44:47], v[144:147], v[174:177], v[44:47]
	v_mfma_f32_16x16x32_f16 v[40:43], v[158:161], v[174:177], v[40:43]
	v_mfma_f32_16x16x32_f16 v[28:31], v[144:147], v[182:185], v[28:31]
	v_mfma_f32_16x16x32_f16 v[24:27], v[158:161], v[182:185], v[24:27]
	v_mfma_f32_16x16x32_f16 v[12:15], v[144:147], v[190:193], v[12:15]
	v_mfma_f32_16x16x32_f16 v[8:11], v[158:161], v[190:193], v[8:11]
	v_mfma_f32_16x16x32_f16 v[60:63], v[154:157], v[170:173], v[60:63]
	v_mfma_f32_16x16x32_f16 v[56:59], v[162:165], v[170:173], v[56:59]
	v_mfma_f32_16x16x32_f16 v[44:47], v[154:157], v[178:181], v[44:47]
	v_mfma_f32_16x16x32_f16 v[40:43], v[162:165], v[178:181], v[40:43]
	v_mfma_f32_16x16x32_f16 v[28:31], v[154:157], v[186:189], v[28:31]
	v_mfma_f32_16x16x32_f16 v[24:27], v[162:165], v[186:189], v[24:27]
	v_mfma_f32_16x16x32_f16 v[12:15], v[154:157], v[194:197], v[12:15]
	v_mfma_f32_16x16x32_f16 v[8:11], v[162:165], v[194:197], v[8:11]
	s_setprio 0
	s_barrier
	s_add_u32 s18, s18, 0x80080
	s_addc_u32 s19, s19, 0
	s_add_i32 s20, s20, s23
	v_lshl_add_u64 v[144:145], s[18:19], 0, v[130:131]
	s_mov_b32 m0, s20
	s_nop 0
	global_load_lds_dwordx4 v[144:145], off
	v_lshl_add_u64 v[144:145], s[18:19], 0, v[134:135]
	s_add_i32 m0, s20, 0x2000
	s_nop 0
	global_load_lds_dwordx4 v[144:145], off
	s_waitcnt vmcnt(6)
	s_barrier
	s_setprio 1
	v_mfma_f32_16x16x32_f16 v[52:55], v[198:201], v[166:169], v[52:55]
	v_mfma_f32_16x16x32_f16 v[48:51], v[206:209], v[166:169], v[48:51]
	v_mfma_f32_16x16x32_f16 v[36:39], v[198:201], v[174:177], v[36:39]
	v_mfma_f32_16x16x32_f16 v[32:35], v[206:209], v[174:177], v[32:35]
	v_mfma_f32_16x16x32_f16 v[20:23], v[198:201], v[182:185], v[20:23]
	v_mfma_f32_16x16x32_f16 v[16:19], v[206:209], v[182:185], v[16:19]
	v_mfma_f32_16x16x32_f16 v[4:7], v[198:201], v[190:193], v[4:7]
	v_mfma_f32_16x16x32_f16 v[0:3], v[206:209], v[190:193], v[0:3]
	v_mfma_f32_16x16x32_f16 v[52:55], v[202:205], v[170:173], v[52:55]
	v_mfma_f32_16x16x32_f16 v[48:51], v[210:213], v[170:173], v[48:51]
	v_mfma_f32_16x16x32_f16 v[36:39], v[202:205], v[178:181], v[36:39]
	v_mfma_f32_16x16x32_f16 v[32:35], v[210:213], v[178:181], v[32:35]
	v_mfma_f32_16x16x32_f16 v[20:23], v[202:205], v[186:189], v[20:23]
	v_mfma_f32_16x16x32_f16 v[16:19], v[210:213], v[186:189], v[16:19]
	v_mfma_f32_16x16x32_f16 v[4:7], v[202:205], v[194:197], v[4:7]
	v_mfma_f32_16x16x32_f16 v[0:3], v[210:213], v[194:197], v[0:3]
	s_setprio 0
	s_add_i32 s78, s78, 2
	s_add_u32 s16, s16, 0x100
	s_addc_u32 s17, s17, 0
	s_add_u32 s76, s76, 0x100
	s_addc_u32 s77, s77, 0
	s_cmp_gt_u32 s78, 29
	s_barrier
	s_cbranch_scc0 .LBB0_197
	v_readlane_b32 s52, v254, 21
	v_readlane_b32 s54, v254, 23
	v_readlane_b32 s55, v254, 24
	v_lshl_add_u32 v154, s14, 8, v148
	v_lshl_or_b32 v144, s4, 8, v150
	v_mov_b64_e32 v[146:147], s[54:55]
	v_mad_i64_i32 v[146:147], s[4:5], v154, s70, v[146:147]
	v_cmp_gt_i32_e32 vcc, s71, v144
	v_ashrrev_i32_e32 v145, 31, v144
	v_readlane_b32 s53, v254, 22
	v_readlane_b32 s56, v254, 25
	v_readlane_b32 s57, v254, 26
	v_readlane_b32 s58, v254, 27
	v_readlane_b32 s59, v254, 28
	v_readlane_b32 s60, v254, 29
	v_readlane_b32 s61, v254, 30
	v_readlane_b32 s62, v254, 31
	v_readlane_b32 s63, v254, 32
	v_readlane_b32 s64, v254, 33
	v_readlane_b32 s65, v254, 34
	v_readlane_b32 s66, v254, 35
	v_readlane_b32 s67, v254, 36
	s_and_saveexec_b64 s[4:5], vcc
	s_cbranch_execz .LBB0_200
	v_cvt_pk_f16_f32 v123, v122, v123
	v_cvt_pk_f16_f32 v122, v120, v121
	v_cvt_pk_f16_f32 v121, v126, v127
	v_cvt_pk_f16_f32 v120, v124, v125
	v_lshl_add_u64 v[124:125], v[144:145], 1, v[146:147]
	global_store_dwordx4 v[124:125], v[120:123], off

.LBB0_647:
	ds_read_b128 v[80:83], v243
	ds_read_b128 v[88:91], v243 offset:1024
	ds_read_b128 v[96:99], v243 offset:2048
	ds_read_b128 v[100:103], v243 offset:3072
	s_add_u32 s18, s16, 0xfff80080
	s_addc_u32 s19, s17, -1
	s_cmp_eq_u32 s80, 28
	s_cselect_b32 s21, s9, s19
	s_cselect_b32 s20, s31, s18
	s_cselect_b32 s19, s7, s79
	s_cselect_b32 s18, s77, s78
	v_lshl_add_u64 v[176:177], s[16:17], 0, v[212:213]
	s_add_i32 m0, s15, 0xc000
	ds_read_b128 v[120:123], v244
	ds_read_b128 v[132:135], v244 offset:1024
	ds_read_b128 v[136:139], v244 offset:2048
	ds_read_b128 v[148:151], v244 offset:3072
	ds_read_b128 v[152:155], v244 offset:4096
	ds_read_b128 v[156:159], v244 offset:5120
	ds_read_b128 v[160:163], v244 offset:6144
	ds_read_b128 v[172:175], v244 offset:7168
	global_load_lds_dwordx4 v[176:177], off
	v_lshl_add_u64 v[176:177], s[16:17], 0, v[214:215]
	s_add_i32 m0, s15, 0xe000
	s_nop 0
	global_load_lds_dwordx4 v[176:177], off
	s_waitcnt lgkmcnt(8)
	s_barrier
	s_waitcnt lgkmcnt(0)
	s_setprio 1
	v_mfma_f32_16x16x32_f16 v[168:171], v[80:83], v[120:123], v[168:171]
	v_mfma_f32_16x16x32_f16 v[164:167], v[96:99], v[120:123], v[164:167]
	v_mfma_f32_16x16x32_f16 v[128:131], v[80:83], v[136:139], v[128:131]
	v_mfma_f32_16x16x32_f16 v[124:127], v[96:99], v[136:139], v[124:127]
	v_mfma_f32_16x16x32_f16 v[108:111], v[80:83], v[152:155], v[108:111]
	v_mfma_f32_16x16x32_f16 v[104:107], v[96:99], v[152:155], v[104:107]
	v_mfma_f32_16x16x32_f16 v[76:79], v[80:83], v[160:163], v[76:79]
	v_mfma_f32_16x16x32_f16 v[72:75], v[96:99], v[160:163], v[72:75]
	v_mfma_f32_16x16x32_f16 v[168:171], v[88:91], v[132:135], v[168:171]
	v_mfma_f32_16x16x32_f16 v[164:167], v[100:103], v[132:135], v[164:167]
	v_mfma_f32_16x16x32_f16 v[128:131], v[88:91], v[148:151], v[128:131]
	v_mfma_f32_16x16x32_f16 v[124:127], v[100:103], v[148:151], v[124:127]
	v_mfma_f32_16x16x32_f16 v[108:111], v[88:91], v[156:159], v[108:111]
	v_mfma_f32_16x16x32_f16 v[104:107], v[100:103], v[156:159], v[104:107]
	v_mfma_f32_16x16x32_f16 v[76:79], v[88:91], v[172:175], v[76:79]
	v_mfma_f32_16x16x32_f16 v[72:75], v[100:103], v[172:175], v[72:75]
	s_setprio 0
	s_barrier
	s_add_i32 s81, s71, s24
	v_lshl_add_u64 v[196:197], s[18:19], 0, v[206:207]
	s_mov_b32 m0, s81
	ds_read_b128 v[176:179], v245
	ds_read_b128 v[180:183], v245 offset:1024
	ds_read_b128 v[184:187], v245 offset:2048
	ds_read_b128 v[188:191], v245 offset:3072
	global_load_lds_dwordx4 v[196:197], off
	v_lshl_add_u64 v[198:199], s[18:19], 0, v[210:211]
	s_add_i32 m0, s81, 0x2000
	s_nop 0
	global_load_lds_dwordx4 v[198:199], off
	s_barrier
	s_waitcnt lgkmcnt(0)
	s_setprio 1
	v_mfma_f32_16x16x32_f16 v[144:147], v[176:179], v[120:123], v[144:147]
	v_mfma_f32_16x16x32_f16 v[116:119], v[176:179], v[136:139], v[116:119]
	v_mfma_f32_16x16x32_f16 v[112:115], v[184:187], v[136:139], v[112:115]
	v_mfma_f32_16x16x32_f16 v[92:95], v[176:179], v[152:155], v[92:95]
	v_mfma_f32_16x16x32_f16 v[84:87], v[184:187], v[152:155], v[84:87]
	v_mfma_f32_16x16x32_f16 v[68:71], v[176:179], v[160:163], v[68:71]
	v_mfma_f32_16x16x32_f16 v[64:67], v[184:187], v[160:163], v[64:67]
	v_mfma_f32_16x16x32_f16 v[144:147], v[180:183], v[132:135], v[144:147]
	v_mfma_f32_16x16x32_f16 v[120:123], v[184:187], v[120:123], v[140:143]
	v_mfma_f32_16x16x32_f16 v[116:119], v[180:183], v[148:151], v[116:119]
	v_mfma_f32_16x16x32_f16 v[112:115], v[188:191], v[148:151], v[112:115]
	v_mfma_f32_16x16x32_f16 v[92:95], v[180:183], v[156:159], v[92:95]
	v_mfma_f32_16x16x32_f16 v[84:87], v[188:191], v[156:159], v[84:87]
	v_mfma_f32_16x16x32_f16 v[68:71], v[180:183], v[172:175], v[68:71]
	v_mfma_f32_16x16x32_f16 v[64:67], v[188:191], v[172:175], v[64:67]
	v_mfma_f32_16x16x32_f16 v[120:123], v[188:191], v[132:135], v[120:123]
	s_setprio 0
	s_mov_b32 m0, s15
	v_lshl_add_u64 v[200:201], s[20:21], 0, v[204:205]
	s_barrier
	ds_read_b128 v[132:135], v244 offset:16384
	ds_read_b128 v[136:139], v244 offset:17408
	ds_read_b128 v[140:143], v244 offset:18432
	ds_read_b128 v[148:151], v244 offset:19456
	ds_read_b128 v[152:155], v244 offset:20480
	ds_read_b128 v[156:159], v244 offset:21504
	ds_read_b128 v[160:163], v244 offset:22528
	ds_read_b128 v[172:175], v244 offset:23552
	global_load_lds_dwordx4 v[200:201], off
	v_lshl_add_u64 v[202:203], s[20:21], 0, v[208:209]
	s_mov_b32 m0, s25
	s_nop 0
	global_load_lds_dwordx4 v[202:203], off
	s_barrier
	s_waitcnt lgkmcnt(0)
	s_setprio 1
	v_mfma_f32_16x16x32_f16 v[60:63], v[80:83], v[132:135], v[60:63]
	v_mfma_f32_16x16x32_f16 v[56:59], v[96:99], v[132:135], v[56:59]
	v_mfma_f32_16x16x32_f16 v[44:47], v[80:83], v[140:143], v[44:47]
	v_mfma_f32_16x16x32_f16 v[40:43], v[96:99], v[140:143], v[40:43]
	v_mfma_f32_16x16x32_f16 v[28:31], v[80:83], v[152:155], v[28:31]
	v_mfma_f32_16x16x32_f16 v[24:27], v[96:99], v[152:155], v[24:27]
	v_mfma_f32_16x16x32_f16 v[12:15], v[80:83], v[160:163], v[12:15]
	v_mfma_f32_16x16x32_f16 v[8:11], v[96:99], v[160:163], v[8:11]
	v_mfma_f32_16x16x32_f16 v[60:63], v[88:91], v[136:139], v[60:63]
	v_mfma_f32_16x16x32_f16 v[56:59], v[100:103], v[136:139], v[56:59]
	v_mfma_f32_16x16x32_f16 v[44:47], v[88:91], v[148:151], v[44:47]
	v_mfma_f32_16x16x32_f16 v[40:43], v[100:103], v[148:151], v[40:43]
	v_mfma_f32_16x16x32_f16 v[28:31], v[88:91], v[156:159], v[28:31]
	v_mfma_f32_16x16x32_f16 v[24:27], v[100:103], v[156:159], v[24:27]
	v_mfma_f32_16x16x32_f16 v[12:15], v[88:91], v[172:175], v[12:15]
	v_mfma_f32_16x16x32_f16 v[8:11], v[100:103], v[172:175], v[8:11]
	s_setprio 0
	s_barrier
	s_add_u32 s82, s18, 0x80000
	s_addc_u32 s83, s19, 0
	s_add_i32 s81, s76, s24
	v_lshl_add_u64 v[80:81], s[82:83], 0, v[206:207]
	s_mov_b32 m0, s81
	s_nop 0
	global_load_lds_dwordx4 v[80:81], off
	v_lshl_add_u64 v[80:81], s[82:83], 0, v[210:211]
	s_add_i32 m0, s81, 0x2000
	s_nop 0
	global_load_lds_dwordx4 v[80:81], off
	s_waitcnt vmcnt(6)
	s_barrier
	s_setprio 1
	v_mfma_f32_16x16x32_f16 v[52:55], v[176:179], v[132:135], v[52:55]
	v_mfma_f32_16x16x32_f16 v[48:51], v[184:187], v[132:135], v[48:51]
	v_mfma_f32_16x16x32_f16 v[36:39], v[176:179], v[140:143], v[36:39]
	v_mfma_f32_16x16x32_f16 v[32:35], v[184:187], v[140:143], v[32:35]
	v_mfma_f32_16x16x32_f16 v[20:23], v[176:179], v[152:155], v[20:23]
	v_mfma_f32_16x16x32_f16 v[16:19], v[184:187], v[152:155], v[16:19]
	v_mfma_f32_16x16x32_f16 v[4:7], v[176:179], v[160:163], v[4:7]
	v_mfma_f32_16x16x32_f16 v[0:3], v[184:187], v[160:163], v[0:3]
	v_mfma_f32_16x16x32_f16 v[52:55], v[180:183], v[136:139], v[52:55]
	v_mfma_f32_16x16x32_f16 v[48:51], v[188:191], v[136:139], v[48:51]
	v_mfma_f32_16x16x32_f16 v[36:39], v[180:183], v[148:151], v[36:39]
	v_mfma_f32_16x16x32_f16 v[32:35], v[188:191], v[148:151], v[32:35]
	v_mfma_f32_16x16x32_f16 v[20:23], v[180:183], v[156:159], v[20:23]
	v_mfma_f32_16x16x32_f16 v[16:19], v[188:191], v[156:159], v[16:19]
	v_mfma_f32_16x16x32_f16 v[4:7], v[180:183], v[172:175], v[4:7]
	v_mfma_f32_16x16x32_f16 v[0:3], v[188:191], v[172:175], v[0:3]
	s_setprio 0
	s_add_i32 s81, 0, 0x18000
	v_add_u32_e32 v100, s81, v241
	s_barrier
	ds_read_b128 v[80:83], v100
	ds_read_b128 v[88:91], v100 offset:1024
	ds_read_b128 v[96:99], v100 offset:2048
	ds_read_b128 v[100:103], v100 offset:3072
	s_add_u32 s20, s20, 0x80000
	s_addc_u32 s21, s21, 0
	s_mov_b32 m0, s26
	v_lshl_add_u64 v[140:141], s[20:21], 0, v[204:205]
	ds_read_b128 v[132:135], v244 offset:32768
	ds_read_b128 v[136:139], v244 offset:33792
	ds_read_b128 v[148:151], v244 offset:34816
	ds_read_b128 v[152:155], v244 offset:35840
	ds_read_b128 v[156:159], v244 offset:36864
	ds_read_b128 v[160:163], v244 offset:37888
	ds_read_b128 v[172:175], v244 offset:38912
	ds_read_b128 v[176:179], v244 offset:39936
	global_load_lds_dwordx4 v[140:141], off
	v_lshl_add_u64 v[140:141], s[20:21], 0, v[208:209]
	s_mov_b32 m0, s27
	s_nop 0
	global_load_lds_dwordx4 v[140:141], off
	s_waitcnt lgkmcnt(8)
	s_barrier
	s_waitcnt lgkmcnt(0)
	s_setprio 1
	v_mfma_f32_16x16x32_f16 v[140:143], v[80:83], v[132:135], v[168:171]
	v_mfma_f32_16x16x32_f16 v[168:171], v[88:91], v[136:139], v[140:143]
	v_mfma_f32_16x16x32_f16 v[140:143], v[96:99], v[132:135], v[164:167]
	v_mfma_f32_16x16x32_f16 v[128:131], v[80:83], v[148:151], v[128:131]
	v_mfma_f32_16x16x32_f16 v[124:127], v[96:99], v[148:151], v[124:127]
	v_mfma_f32_16x16x32_f16 v[108:111], v[80:83], v[156:159], v[108:111]
	v_mfma_f32_16x16x32_f16 v[104:107], v[96:99], v[156:159], v[104:107]
	v_mfma_f32_16x16x32_f16 v[76:79], v[80:83], v[172:175], v[76:79]
	v_mfma_f32_16x16x32_f16 v[72:75], v[96:99], v[172:175], v[72:75]
	v_mfma_f32_16x16x32_f16 v[164:167], v[100:103], v[136:139], v[140:143]
	v_mfma_f32_16x16x32_f16 v[128:131], v[88:91], v[152:155], v[128:131]
	v_mfma_f32_16x16x32_f16 v[124:127], v[100:103], v[152:155], v[124:127]
	v_mfma_f32_16x16x32_f16 v[108:111], v[88:91], v[160:163], v[108:111]
	v_mfma_f32_16x16x32_f16 v[104:107], v[100:103], v[160:163], v[104:107]
	v_mfma_f32_16x16x32_f16 v[76:79], v[88:91], v[176:179], v[76:79]
	v_mfma_f32_16x16x32_f16 v[72:75], v[100:103], v[176:179], v[72:75]
	s_setprio 0
	s_barrier
	s_add_i32 s20, 0, 0x1c000
	v_add_u32_e32 v140, s20, v241
	s_add_i32 s21, s81, s24
	ds_read_b128 v[180:183], v140
	ds_read_b128 v[184:187], v140 offset:1024
	ds_read_b128 v[188:191], v140 offset:2048
	ds_read_b128 v[192:195], v140 offset:3072
	v_lshl_add_u64 v[140:141], v[196:197], 0, s[4:5]
	s_mov_b32 m0, s21
	s_nop 0
	global_load_lds_dwordx4 v[140:141], off
	v_lshl_add_u64 v[140:141], v[198:199], 0, s[4:5]
	s_add_i32 m0, s21, 0x2000
	s_nop 0
	global_load_lds_dwordx4 v[140:141], off
	s_barrier
	s_waitcnt lgkmcnt(0)
	s_setprio 1
	v_mfma_f32_16x16x32_f16 v[140:143], v[180:183], v[132:135], v[144:147]
	v_mfma_f32_16x16x32_f16 v[120:123], v[188:191], v[132:135], v[120:123]
	v_mfma_f32_16x16x32_f16 v[116:119], v[180:183], v[148:151], v[116:119]
	v_mfma_f32_16x16x32_f16 v[112:115], v[188:191], v[148:151], v[112:115]
	v_mfma_f32_16x16x32_f16 v[92:95], v[180:183], v[156:159], v[92:95]
	v_mfma_f32_16x16x32_f16 v[84:87], v[188:191], v[156:159], v[84:87]
	v_mfma_f32_16x16x32_f16 v[68:71], v[180:183], v[172:175], v[68:71]
	v_mfma_f32_16x16x32_f16 v[64:67], v[188:191], v[172:175], v[64:67]
	v_mfma_f32_16x16x32_f16 v[144:147], v[184:187], v[136:139], v[140:143]
	v_mfma_f32_16x16x32_f16 v[140:143], v[192:195], v[136:139], v[120:123]
	v_mfma_f32_16x16x32_f16 v[116:119], v[184:187], v[152:155], v[116:119]
	v_mfma_f32_16x16x32_f16 v[112:115], v[192:195], v[152:155], v[112:115]
	v_mfma_f32_16x16x32_f16 v[92:95], v[184:187], v[160:163], v[92:95]
	v_mfma_f32_16x16x32_f16 v[84:87], v[192:195], v[160:163], v[84:87]
	v_mfma_f32_16x16x32_f16 v[68:71], v[184:187], v[176:179], v[68:71]
	v_mfma_f32_16x16x32_f16 v[64:67], v[192:195], v[176:179], v[64:67]
	s_setprio 0
	s_mov_b32 m0, s35
	v_lshl_add_u64 v[176:177], v[200:201], 0, s[4:5]
	s_barrier
	ds_read_b128 v[120:123], v244 offset:49152
	ds_read_b128 v[132:135], v244 offset:50176
	ds_read_b128 v[136:139], v244 offset:51200
	ds_read_b128 v[148:151], v244 offset:52224
	ds_read_b128 v[152:155], v244 offset:53248
	ds_read_b128 v[156:159], v244 offset:54272
	ds_read_b128 v[160:163], v244 offset:55296
	ds_read_b128 v[172:175], v244 offset:56320
	global_load_lds_dwordx4 v[176:177], off
	v_lshl_add_u64 v[176:177], v[202:203], 0, s[4:5]
	s_mov_b32 m0, s68
	s_nop 0
	global_load_lds_dwordx4 v[176:177], off
	s_barrier
	s_waitcnt lgkmcnt(0)
	s_setprio 1
	v_mfma_f32_16x16x32_f16 v[60:63], v[80:83], v[120:123], v[60:63]
	v_mfma_f32_16x16x32_f16 v[56:59], v[96:99], v[120:123], v[56:59]
	v_mfma_f32_16x16x32_f16 v[44:47], v[80:83], v[136:139], v[44:47]
	v_mfma_f32_16x16x32_f16 v[40:43], v[96:99], v[136:139], v[40:43]
	v_mfma_f32_16x16x32_f16 v[28:31], v[80:83], v[152:155], v[28:31]
	v_mfma_f32_16x16x32_f16 v[24:27], v[96:99], v[152:155], v[24:27]
	v_mfma_f32_16x16x32_f16 v[12:15], v[80:83], v[160:163], v[12:15]
	v_mfma_f32_16x16x32_f16 v[8:11], v[96:99], v[160:163], v[8:11]
	v_mfma_f32_16x16x32_f16 v[60:63], v[88:91], v[132:135], v[60:63]
	v_mfma_f32_16x16x32_f16 v[56:59], v[100:103], v[132:135], v[56:59]
	v_mfma_f32_16x16x32_f16 v[44:47], v[88:91], v[148:151], v[44:47]
	v_mfma_f32_16x16x32_f16 v[40:43], v[100:103], v[148:151], v[40:43]
	v_mfma_f32_16x16x32_f16 v[28:31], v[88:91], v[156:159], v[28:31]
	v_mfma_f32_16x16x32_f16 v[24:27], v[100:103], v[156:159], v[24:27]
	v_mfma_f32_16x16x32_f16 v[12:15], v[88:91], v[172:175], v[12:15]
	v_mfma_f32_16x16x32_f16 v[8:11], v[100:103], v[172:175], v[8:11]
	s_setprio 0
	s_barrier
	s_add_u32 s18, s18, 0x80080
	s_addc_u32 s19, s19, 0
	s_add_i32 s20, s20, s24
	v_lshl_add_u64 v[80:81], s[18:19], 0, v[206:207]
	s_mov_b32 m0, s20
	s_nop 0
	global_load_lds_dwordx4 v[80:81], off
	v_lshl_add_u64 v[80:81], s[18:19], 0, v[210:211]
	s_add_i32 m0, s20, 0x2000
	s_nop 0
	global_load_lds_dwordx4 v[80:81], off
	s_waitcnt vmcnt(6)
	s_barrier
	s_setprio 1
	v_mfma_f32_16x16x32_f16 v[52:55], v[180:183], v[120:123], v[52:55]
	v_mfma_f32_16x16x32_f16 v[48:51], v[188:191], v[120:123], v[48:51]
	v_mfma_f32_16x16x32_f16 v[36:39], v[180:183], v[136:139], v[36:39]
	v_mfma_f32_16x16x32_f16 v[32:35], v[188:191], v[136:139], v[32:35]
	v_mfma_f32_16x16x32_f16 v[20:23], v[180:183], v[152:155], v[20:23]
	v_mfma_f32_16x16x32_f16 v[16:19], v[188:191], v[152:155], v[16:19]
	v_mfma_f32_16x16x32_f16 v[4:7], v[180:183], v[160:163], v[4:7]
	v_mfma_f32_16x16x32_f16 v[0:3], v[188:191], v[160:163], v[0:3]
	v_mfma_f32_16x16x32_f16 v[52:55], v[184:187], v[132:135], v[52:55]
	v_mfma_f32_16x16x32_f16 v[48:51], v[192:195], v[132:135], v[48:51]
	v_mfma_f32_16x16x32_f16 v[36:39], v[184:187], v[148:151], v[36:39]
	v_mfma_f32_16x16x32_f16 v[32:35], v[192:195], v[148:151], v[32:35]
	v_mfma_f32_16x16x32_f16 v[20:23], v[184:187], v[156:159], v[20:23]
	v_mfma_f32_16x16x32_f16 v[16:19], v[192:195], v[156:159], v[16:19]
	v_mfma_f32_16x16x32_f16 v[4:7], v[184:187], v[172:175], v[4:7]
	v_mfma_f32_16x16x32_f16 v[0:3], v[192:195], v[172:175], v[0:3]
	s_setprio 0
	s_add_i32 s80, s80, 2
	s_add_u32 s16, s16, 0x100
	s_addc_u32 s17, s17, 0
	s_add_u32 s78, s78, 0x100
	s_addc_u32 s79, s79, 0
	s_cmp_gt_u32 s80, 29
	s_barrier
	s_cbranch_scc0 .LBB0_647
	s_lshl_b32 s7, s14, 8
	s_add_i32 s9, s7, 0xffffe000
	s_lshr_b32 s9, s9, 11
	s_mulk_i32 s9, 0x1800
	s_addk_i32 s9, 0x1800
	s_cmp_gt_i32 s14, 31
	s_cselect_b32 s16, s9, 0
	s_ashr_i32 s17, s16, 31
	v_lshl_or_b32 v120, s30, 8, v242
	s_lshl_b64 s[16:17], s[16:17], 2
	s_add_u32 s16, s29, s16
	v_ashrrev_i32_e32 v121, 31, v120
	v_add_u32_e32 v122, s7, v240
	s_addc_u32 s17, s34, s17
	v_lshlrev_b64 v[220:221], 1, v[120:121]
	v_ashrrev_i32_e32 v123, 31, v122
	v_lshl_add_u64 v[88:89], v[120:121], 2, s[16:17]
	v_lshl_add_u64 v[120:121], s[40:41], 0, v[220:221]
	v_lshlrev_b64 v[236:237], 12, v[122:123]
	v_lshl_add_u64 v[132:133], v[120:121], 0, v[236:237]
	global_load_dwordx4 v[96:99], v[88:89], off offset:16
	global_load_dwordx4 v[100:103], v[88:89], off
	global_load_dwordx4 v[80:83], v[88:89], off offset:528
	s_nop 0
	global_load_dwordx4 v[88:91], v[88:89], off offset:512
	s_nop 0
	global_load_dwordx4 v[246:249], v[132:133], off nt
	global_load_dwordx4 v[200:203], v[132:133], off offset:256 nt
	v_or_b32_e32 v132, 16, v122
	v_ashrrev_i32_e32 v133, 31, v132
	v_lshlrev_b64 v[234:235], 12, v[132:133]
	v_lshl_add_u64 v[132:133], v[120:121], 0, v[234:235]
	global_load_dwordx4 v[196:199], v[132:133], off nt
	global_load_dwordx4 v[192:195], v[132:133], off offset:256 nt
	v_or_b32_e32 v132, 32, v122
	v_ashrrev_i32_e32 v133, 31, v132
	v_lshlrev_b64 v[232:233], 12, v[132:133]
	v_lshl_add_u64 v[132:133], v[120:121], 0, v[232:233]
	global_load_dwordx4 v[188:191], v[132:133], off nt
	global_load_dwordx4 v[184:187], v[132:133], off offset:256 nt
	v_or_b32_e32 v122, 48, v122
	v_ashrrev_i32_e32 v123, 31, v122
	v_lshlrev_b64 v[230:231], 12, v[122:123]
	v_lshl_add_u64 v[122:123], v[120:121], 0, v[230:231]
	global_load_dwordx4 v[180:183], v[122:123], off nt
	global_load_dwordx4 v[176:179], v[122:123], off offset:256 nt
	s_mov_b64 s[16:17], 0x80000
	v_lshl_add_u64 v[228:229], v[236:237], 0, s[16:17]
	v_lshl_add_u64 v[122:123], v[120:121], 0, v[228:229]
	global_load_dwordx4 v[172:175], v[122:123], off nt
	global_load_dwordx4 v[160:163], v[122:123], off offset:256 nt
	s_mov_b64 s[16:17], 0x90000
	v_lshl_add_u64 v[226:227], v[236:237], 0, s[16:17]
	v_lshl_add_u64 v[122:123], v[120:121], 0, v[226:227]
	global_load_dwordx4 v[156:159], v[122:123], off nt
	global_load_dwordx4 v[152:155], v[122:123], off offset:256 nt
	s_mov_b64 s[16:17], 0xa0000
	v_lshl_add_u64 v[224:225], v[236:237], 0, s[16:17]
	v_lshl_add_u64 v[122:123], v[120:121], 0, v[224:225]
	global_load_dwordx4 v[148:151], v[122:123], off nt
	global_load_dwordx4 v[136:139], v[122:123], off offset:256 nt
	s_mov_b64 s[16:17], 0xb0000
	v_lshl_add_u64 v[222:223], v[236:237], 0, s[16:17]
	v_lshl_add_u64 v[120:121], v[120:121], 0, v[222:223]
	global_load_dwordx4 v[132:135], v[120:121], off nt
	s_nop 0
	global_load_dwordx4 v[120:123], v[120:121], off offset:256 nt
	s_and_b64 vcc, exec, s[2:3]
	s_mov_b32 s30, s6
	s_mov_b32 s14, s8
	s_mov_b64 s[18:19], s[12:13]
	s_mov_b64 s[16:17], s[10:11]
	s_waitcnt vmcnt(0)
	v_cvt_f32_f16_e32 v250, v246
	v_cvt_f32_f16_sdwa v251, v246 dst_sel:DWORD dst_unused:UNUSED_PAD src0_sel:WORD_1
	v_pk_fma_f32 v[168:169], v[168:169], v[100:101], v[250:251]
	s_nop 0
	v_cvt_pk_f16_f32 v246, v168, v169
	v_cvt_f32_f16_e32 v168, v248
	v_cvt_f32_f16_sdwa v169, v248 dst_sel:DWORD dst_unused:UNUSED_PAD src0_sel:WORD_1
	v_pk_fma_f32 v[164:165], v[164:165], v[96:97], v[168:169]
	s_nop 0
	v_cvt_pk_f16_f32 v248, v164, v165
	v_cvt_f32_f16_e32 v164, v247
	v_cvt_f32_f16_sdwa v165, v247 dst_sel:DWORD dst_unused:UNUSED_PAD src0_sel:WORD_1
	v_pk_fma_f32 v[164:165], v[170:171], v[102:103], v[164:165]
	s_nop 0
	v_cvt_pk_f16_f32 v247, v164, v165
	v_cvt_f32_f16_e32 v164, v249
	v_cvt_f32_f16_sdwa v165, v249 dst_sel:DWORD dst_unused:UNUSED_PAD src0_sel:WORD_1
	v_pk_fma_f32 v[164:165], v[166:167], v[98:99], v[164:165]
	s_nop 0
	v_cvt_pk_f16_f32 v249, v164, v165
	v_lshl_add_u64 v[164:165], s[0:1], 0, v[236:237]
	v_lshl_add_u64 v[168:169], v[164:165], 0, v[220:221]
	v_cvt_f32_f16_e32 v164, v200
	v_cvt_f32_f16_sdwa v165, v200 dst_sel:DWORD dst_unused:UNUSED_PAD src0_sel:WORD_1
	global_store_dwordx4 v[168:169], v[246:249], off
	v_pk_fma_f32 v[144:145], v[144:145], v[88:89], v[164:165]
	s_nop 0
	v_cvt_pk_f16_f32 v164, v144, v145
	v_cvt_f32_f16_e32 v144, v202
	v_cvt_f32_f16_sdwa v145, v202 dst_sel:DWORD dst_unused:UNUSED_PAD src0_sel:WORD_1
	v_pk_fma_f32 v[140:141], v[140:141], v[80:81], v[144:145]
	s_nop 0
	v_cvt_pk_f16_f32 v166, v140, v141
	v_cvt_f32_f16_e32 v140, v201
	v_cvt_f32_f16_sdwa v141, v201 dst_sel:DWORD dst_unused:UNUSED_PAD src0_sel:WORD_1
	v_pk_fma_f32 v[140:141], v[146:147], v[90:91], v[140:141]
	s_nop 0
	v_cvt_pk_f16_f32 v165, v140, v141
	v_cvt_f32_f16_e32 v140, v203
	v_cvt_f32_f16_sdwa v141, v203 dst_sel:DWORD dst_unused:UNUSED_PAD src0_sel:WORD_1
	v_pk_fma_f32 v[140:141], v[142:143], v[82:83], v[140:141]
	s_nop 0
	v_cvt_pk_f16_f32 v167, v140, v141
	v_cvt_f32_f16_e32 v140, v196
	v_cvt_f32_f16_sdwa v141, v196 dst_sel:DWORD dst_unused:UNUSED_PAD src0_sel:WORD_1
	global_store_dwordx4 v[168:169], v[164:167], off offset:256
	v_pk_fma_f32 v[128:129], v[128:129], v[100:101], v[140:141]
	s_nop 0
	v_cvt_pk_f16_f32 v140, v128, v129
	v_cvt_f32_f16_e32 v128, v198
	v_cvt_f32_f16_sdwa v129, v198 dst_sel:DWORD dst_unused:UNUSED_PAD src0_sel:WORD_1
	v_pk_fma_f32 v[124:125], v[124:125], v[96:97], v[128:129]
	s_nop 0
	v_cvt_pk_f16_f32 v142, v124, v125
	v_cvt_f32_f16_e32 v124, v197
	v_cvt_f32_f16_sdwa v125, v197 dst_sel:DWORD dst_unused:UNUSED_PAD src0_sel:WORD_1
	v_pk_fma_f32 v[124:125], v[130:131], v[102:103], v[124:125]
	s_nop 0
	v_cvt_pk_f16_f32 v141, v124, v125
	v_cvt_f32_f16_e32 v124, v199
	v_cvt_f32_f16_sdwa v125, v199 dst_sel:DWORD dst_unused:UNUSED_PAD src0_sel:WORD_1
	v_pk_fma_f32 v[124:125], v[126:127], v[98:99], v[124:125]
	s_nop 0
	v_cvt_pk_f16_f32 v143, v124, v125
	v_lshl_add_u64 v[124:125], s[0:1], 0, v[234:235]
	v_lshl_add_u64 v[128:129], v[124:125], 0, v[220:221]
	v_cvt_f32_f16_e32 v124, v192
	v_cvt_f32_f16_sdwa v125, v192 dst_sel:DWORD dst_unused:UNUSED_PAD src0_sel:WORD_1
	global_store_dwordx4 v[128:129], v[140:143], off
	v_pk_fma_f32 v[116:117], v[116:117], v[88:89], v[124:125]
	s_nop 0
	v_cvt_pk_f16_f32 v124, v116, v117
	v_cvt_f32_f16_e32 v116, v194
	v_cvt_f32_f16_sdwa v117, v194 dst_sel:DWORD dst_unused:UNUSED_PAD src0_sel:WORD_1
	v_pk_fma_f32 v[112:113], v[112:113], v[80:81], v[116:117]
	s_nop 0
	v_cvt_pk_f16_f32 v126, v112, v113
	v_cvt_f32_f16_e32 v112, v193
	v_cvt_f32_f16_sdwa v113, v193 dst_sel:DWORD dst_unused:UNUSED_PAD src0_sel:WORD_1
	v_pk_fma_f32 v[112:113], v[118:119], v[90:91], v[112:113]
	s_nop 0
	v_cvt_pk_f16_f32 v125, v112, v113
	v_cvt_f32_f16_e32 v112, v195
	v_cvt_f32_f16_sdwa v113, v195 dst_sel:DWORD dst_unused:UNUSED_PAD src0_sel:WORD_1
	v_pk_fma_f32 v[112:113], v[114:115], v[82:83], v[112:113]
	s_nop 0
	v_cvt_pk_f16_f32 v127, v112, v113
	v_cvt_f32_f16_e32 v112, v188
	v_cvt_f32_f16_sdwa v113, v188 dst_sel:DWORD dst_unused:UNUSED_PAD src0_sel:WORD_1
	global_store_dwordx4 v[128:129], v[124:127], off offset:256
	v_pk_fma_f32 v[108:109], v[108:109], v[100:101], v[112:113]
	s_nop 0
	v_cvt_pk_f16_f32 v112, v108, v109
	v_cvt_f32_f16_e32 v108, v190
	v_cvt_f32_f16_sdwa v109, v190 dst_sel:DWORD dst_unused:UNUSED_PAD src0_sel:WORD_1
	v_pk_fma_f32 v[104:105], v[104:105], v[96:97], v[108:109]
	s_nop 0
	v_cvt_pk_f16_f32 v114, v104, v105
	v_cvt_f32_f16_e32 v104, v189
	v_cvt_f32_f16_sdwa v105, v189 dst_sel:DWORD dst_unused:UNUSED_PAD src0_sel:WORD_1
	v_pk_fma_f32 v[104:105], v[110:111], v[102:103], v[104:105]
	s_nop 0
	v_cvt_pk_f16_f32 v113, v104, v105
	v_cvt_f32_f16_e32 v104, v191
	v_cvt_f32_f16_sdwa v105, v191 dst_sel:DWORD dst_unused:UNUSED_PAD src0_sel:WORD_1
	v_pk_fma_f32 v[104:105], v[106:107], v[98:99], v[104:105]
	s_nop 0
	v_cvt_pk_f16_f32 v115, v104, v105
	v_lshl_add_u64 v[104:105], s[0:1], 0, v[232:233]
	v_lshl_add_u64 v[108:109], v[104:105], 0, v[220:221]
	v_cvt_f32_f16_e32 v104, v184
	v_cvt_f32_f16_sdwa v105, v184 dst_sel:DWORD dst_unused:UNUSED_PAD src0_sel:WORD_1
	global_store_dwordx4 v[108:109], v[112:115], off
	v_pk_fma_f32 v[92:93], v[92:93], v[88:89], v[104:105]
	s_nop 0
	v_cvt_pk_f16_f32 v104, v92, v93
	v_cvt_f32_f16_e32 v92, v186
	v_cvt_f32_f16_sdwa v93, v186 dst_sel:DWORD dst_unused:UNUSED_PAD src0_sel:WORD_1
	v_pk_fma_f32 v[84:85], v[84:85], v[80:81], v[92:93]
	s_nop 0
	v_cvt_pk_f16_f32 v106, v84, v85
	v_cvt_f32_f16_e32 v84, v185
	v_cvt_f32_f16_sdwa v85, v185 dst_sel:DWORD dst_unused:UNUSED_PAD src0_sel:WORD_1
	v_pk_fma_f32 v[84:85], v[94:95], v[90:91], v[84:85]
	s_nop 0
	v_cvt_pk_f16_f32 v105, v84, v85
	v_cvt_f32_f16_e32 v84, v187
	v_cvt_f32_f16_sdwa v85, v187 dst_sel:DWORD dst_unused:UNUSED_PAD src0_sel:WORD_1
	v_pk_fma_f32 v[84:85], v[86:87], v[82:83], v[84:85]
	s_nop 0
	v_cvt_pk_f16_f32 v107, v84, v85
	v_cvt_f32_f16_e32 v84, v180
	v_cvt_f32_f16_sdwa v85, v180 dst_sel:DWORD dst_unused:UNUSED_PAD src0_sel:WORD_1
	global_store_dwordx4 v[108:109], v[104:107], off offset:256
	v_pk_fma_f32 v[76:77], v[76:77], v[100:101], v[84:85]
	s_nop 0
	v_cvt_pk_f16_f32 v84, v76, v77
	v_cvt_f32_f16_e32 v76, v182
	v_cvt_f32_f16_sdwa v77, v182 dst_sel:DWORD dst_unused:UNUSED_PAD src0_sel:WORD_1
	v_pk_fma_f32 v[72:73], v[72:73], v[96:97], v[76:77]
	s_nop 0
	v_cvt_pk_f16_f32 v86, v72, v73
	v_cvt_f32_f16_e32 v72, v181
	v_cvt_f32_f16_sdwa v73, v181 dst_sel:DWORD dst_unused:UNUSED_PAD src0_sel:WORD_1
	v_pk_fma_f32 v[72:73], v[78:79], v[102:103], v[72:73]
	s_nop 0
	v_cvt_pk_f16_f32 v85, v72, v73
	v_cvt_f32_f16_e32 v72, v183
	v_cvt_f32_f16_sdwa v73, v183 dst_sel:DWORD dst_unused:UNUSED_PAD src0_sel:WORD_1
	v_pk_fma_f32 v[72:73], v[74:75], v[98:99], v[72:73]
	s_nop 0
	v_cvt_pk_f16_f32 v87, v72, v73
	v_lshl_add_u64 v[72:73], s[0:1], 0, v[230:231]
	v_lshl_add_u64 v[76:77], v[72:73], 0, v[220:221]
	v_cvt_f32_f16_e32 v72, v176
	v_cvt_f32_f16_sdwa v73, v176 dst_sel:DWORD dst_unused:UNUSED_PAD src0_sel:WORD_1
	global_store_dwordx4 v[76:77], v[84:87], off
	v_pk_fma_f32 v[68:69], v[68:69], v[88:89], v[72:73]
	s_nop 0
	v_cvt_pk_f16_f32 v72, v68, v69
	v_cvt_f32_f16_e32 v68, v178
	v_cvt_f32_f16_sdwa v69, v178 dst_sel:DWORD dst_unused:UNUSED_PAD src0_sel:WORD_1
	v_pk_fma_f32 v[64:65], v[64:65], v[80:81], v[68:69]
	s_nop 0
	v_cvt_pk_f16_f32 v74, v64, v65
	v_cvt_f32_f16_e32 v64, v177
	v_cvt_f32_f16_sdwa v65, v177 dst_sel:DWORD dst_unused:UNUSED_PAD src0_sel:WORD_1
	v_pk_fma_f32 v[64:65], v[70:71], v[90:91], v[64:65]
	s_nop 0
	v_cvt_pk_f16_f32 v73, v64, v65
	v_cvt_f32_f16_e32 v64, v179
	v_cvt_f32_f16_sdwa v65, v179 dst_sel:DWORD dst_unused:UNUSED_PAD src0_sel:WORD_1
	v_pk_fma_f32 v[64:65], v[66:67], v[82:83], v[64:65]
	s_nop 0
	v_cvt_pk_f16_f32 v75, v64, v65
	v_cvt_f32_f16_e32 v64, v172
	v_cvt_f32_f16_sdwa v65, v172 dst_sel:DWORD dst_unused:UNUSED_PAD src0_sel:WORD_1
	global_store_dwordx4 v[76:77], v[72:75], off offset:256
	v_pk_fma_f32 v[60:61], v[60:61], v[100:101], v[64:65]
	s_nop 0
	v_cvt_pk_f16_f32 v64, v60, v61
	v_cvt_f32_f16_e32 v60, v174
	v_cvt_f32_f16_sdwa v61, v174 dst_sel:DWORD dst_unused:UNUSED_PAD src0_sel:WORD_1
	v_pk_fma_f32 v[56:57], v[56:57], v[96:97], v[60:61]
	s_nop 0
	v_cvt_pk_f16_f32 v66, v56, v57
	v_cvt_f32_f16_e32 v56, v173
	v_cvt_f32_f16_sdwa v57, v173 dst_sel:DWORD dst_unused:UNUSED_PAD src0_sel:WORD_1
	v_pk_fma_f32 v[56:57], v[62:63], v[102:103], v[56:57]
	s_nop 0
	v_cvt_pk_f16_f32 v65, v56, v57
	v_cvt_f32_f16_e32 v56, v175
	v_cvt_f32_f16_sdwa v57, v175 dst_sel:DWORD dst_unused:UNUSED_PAD src0_sel:WORD_1
	v_pk_fma_f32 v[56:57], v[58:59], v[98:99], v[56:57]
	s_nop 0
	v_cvt_pk_f16_f32 v67, v56, v57
	v_lshl_add_u64 v[56:57], s[0:1], 0, v[228:229]
	v_lshl_add_u64 v[60:61], v[56:57], 0, v[220:221]
	v_cvt_f32_f16_e32 v56, v160
	v_cvt_f32_f16_sdwa v57, v160 dst_sel:DWORD dst_unused:UNUSED_PAD src0_sel:WORD_1
	global_store_dwordx4 v[60:61], v[64:67], off
	v_pk_fma_f32 v[52:53], v[52:53], v[88:89], v[56:57]
	s_nop 0
	v_cvt_pk_f16_f32 v56, v52, v53
	v_cvt_f32_f16_e32 v52, v162
	v_cvt_f32_f16_sdwa v53, v162 dst_sel:DWORD dst_unused:UNUSED_PAD src0_sel:WORD_1
	v_pk_fma_f32 v[48:49], v[48:49], v[80:81], v[52:53]
	s_nop 0
	v_cvt_pk_f16_f32 v58, v48, v49
	v_cvt_f32_f16_e32 v48, v161
	v_cvt_f32_f16_sdwa v49, v161 dst_sel:DWORD dst_unused:UNUSED_PAD src0_sel:WORD_1
	v_pk_fma_f32 v[48:49], v[54:55], v[90:91], v[48:49]
	s_nop 0
	v_cvt_pk_f16_f32 v57, v48, v49
	v_cvt_f32_f16_e32 v48, v163
	v_cvt_f32_f16_sdwa v49, v163 dst_sel:DWORD dst_unused:UNUSED_PAD src0_sel:WORD_1
	v_pk_fma_f32 v[48:49], v[50:51], v[82:83], v[48:49]
	s_nop 0
	v_cvt_pk_f16_f32 v59, v48, v49
	v_cvt_f32_f16_e32 v48, v156
	v_cvt_f32_f16_sdwa v49, v156 dst_sel:DWORD dst_unused:UNUSED_PAD src0_sel:WORD_1
	global_store_dwordx4 v[60:61], v[56:59], off offset:256
	v_pk_fma_f32 v[44:45], v[44:45], v[100:101], v[48:49]
	s_nop 0
	v_cvt_pk_f16_f32 v48, v44, v45
	v_cvt_f32_f16_e32 v44, v158
	v_cvt_f32_f16_sdwa v45, v158 dst_sel:DWORD dst_unused:UNUSED_PAD src0_sel:WORD_1
	v_pk_fma_f32 v[40:41], v[40:41], v[96:97], v[44:45]
	s_nop 0
	v_cvt_pk_f16_f32 v50, v40, v41
	v_cvt_f32_f16_e32 v40, v157
	v_cvt_f32_f16_sdwa v41, v157 dst_sel:DWORD dst_unused:UNUSED_PAD src0_sel:WORD_1
	v_pk_fma_f32 v[40:41], v[46:47], v[102:103], v[40:41]
	s_nop 0
	v_cvt_pk_f16_f32 v49, v40, v41
	v_cvt_f32_f16_e32 v40, v159
	v_cvt_f32_f16_sdwa v41, v159 dst_sel:DWORD dst_unused:UNUSED_PAD src0_sel:WORD_1
	v_pk_fma_f32 v[40:41], v[42:43], v[98:99], v[40:41]
	s_nop 0
	v_cvt_pk_f16_f32 v51, v40, v41
	v_lshl_add_u64 v[40:41], s[0:1], 0, v[226:227]
	v_lshl_add_u64 v[44:45], v[40:41], 0, v[220:221]
	v_cvt_f32_f16_e32 v40, v152
	v_cvt_f32_f16_sdwa v41, v152 dst_sel:DWORD dst_unused:UNUSED_PAD src0_sel:WORD_1
	global_store_dwordx4 v[44:45], v[48:51], off
	v_pk_fma_f32 v[36:37], v[36:37], v[88:89], v[40:41]
	s_nop 0
	v_cvt_pk_f16_f32 v40, v36, v37
	v_cvt_f32_f16_e32 v36, v154
	v_cvt_f32_f16_sdwa v37, v154 dst_sel:DWORD dst_unused:UNUSED_PAD src0_sel:WORD_1
	v_pk_fma_f32 v[32:33], v[32:33], v[80:81], v[36:37]
	s_nop 0
	v_cvt_pk_f16_f32 v42, v32, v33
	v_cvt_f32_f16_e32 v32, v153
	v_cvt_f32_f16_sdwa v33, v153 dst_sel:DWORD dst_unused:UNUSED_PAD src0_sel:WORD_1
	v_pk_fma_f32 v[32:33], v[38:39], v[90:91], v[32:33]
	s_nop 0
	v_cvt_pk_f16_f32 v41, v32, v33
	v_cvt_f32_f16_e32 v32, v155
	v_cvt_f32_f16_sdwa v33, v155 dst_sel:DWORD dst_unused:UNUSED_PAD src0_sel:WORD_1
	v_pk_fma_f32 v[32:33], v[34:35], v[82:83], v[32:33]
	s_nop 0
	v_cvt_pk_f16_f32 v43, v32, v33
	v_cvt_f32_f16_e32 v32, v148
	v_cvt_f32_f16_sdwa v33, v148 dst_sel:DWORD dst_unused:UNUSED_PAD src0_sel:WORD_1
	global_store_dwordx4 v[44:45], v[40:43], off offset:256
	v_pk_fma_f32 v[28:29], v[28:29], v[100:101], v[32:33]
	s_nop 0
	v_cvt_pk_f16_f32 v32, v28, v29
	v_cvt_f32_f16_e32 v28, v150
	v_cvt_f32_f16_sdwa v29, v150 dst_sel:DWORD dst_unused:UNUSED_PAD src0_sel:WORD_1
	v_pk_fma_f32 v[24:25], v[24:25], v[96:97], v[28:29]
	s_nop 0
	v_cvt_pk_f16_f32 v34, v24, v25
	v_cvt_f32_f16_e32 v24, v149
	v_cvt_f32_f16_sdwa v25, v149 dst_sel:DWORD dst_unused:UNUSED_PAD src0_sel:WORD_1
	v_pk_fma_f32 v[24:25], v[30:31], v[102:103], v[24:25]
	s_nop 0
	v_cvt_pk_f16_f32 v33, v24, v25
	v_cvt_f32_f16_e32 v24, v151
	v_cvt_f32_f16_sdwa v25, v151 dst_sel:DWORD dst_unused:UNUSED_PAD src0_sel:WORD_1
	v_pk_fma_f32 v[24:25], v[26:27], v[98:99], v[24:25]
	s_nop 0
	v_cvt_pk_f16_f32 v35, v24, v25
	v_lshl_add_u64 v[24:25], s[0:1], 0, v[224:225]
	v_lshl_add_u64 v[28:29], v[24:25], 0, v[220:221]
	v_cvt_f32_f16_e32 v24, v136
	v_cvt_f32_f16_sdwa v25, v136 dst_sel:DWORD dst_unused:UNUSED_PAD src0_sel:WORD_1
	global_store_dwordx4 v[28:29], v[32:35], off
	v_pk_fma_f32 v[20:21], v[20:21], v[88:89], v[24:25]
	s_nop 0
	v_cvt_pk_f16_f32 v24, v20, v21
	v_cvt_f32_f16_e32 v20, v138
	v_cvt_f32_f16_sdwa v21, v138 dst_sel:DWORD dst_unused:UNUSED_PAD src0_sel:WORD_1
	v_pk_fma_f32 v[16:17], v[16:17], v[80:81], v[20:21]
	s_nop 0
	v_cvt_pk_f16_f32 v26, v16, v17
	v_cvt_f32_f16_e32 v16, v137
	v_cvt_f32_f16_sdwa v17, v137 dst_sel:DWORD dst_unused:UNUSED_PAD src0_sel:WORD_1
	v_pk_fma_f32 v[16:17], v[22:23], v[90:91], v[16:17]
	s_nop 0
	v_cvt_pk_f16_f32 v25, v16, v17
	v_cvt_f32_f16_e32 v16, v139
	v_cvt_f32_f16_sdwa v17, v139 dst_sel:DWORD dst_unused:UNUSED_PAD src0_sel:WORD_1
	v_pk_fma_f32 v[16:17], v[18:19], v[82:83], v[16:17]
	s_nop 0
	v_cvt_pk_f16_f32 v27, v16, v17
	v_cvt_f32_f16_e32 v16, v132
	v_cvt_f32_f16_sdwa v17, v132 dst_sel:DWORD dst_unused:UNUSED_PAD src0_sel:WORD_1
	global_store_dwordx4 v[28:29], v[24:27], off offset:256
	v_pk_fma_f32 v[12:13], v[12:13], v[100:101], v[16:17]
	s_nop 0
	v_cvt_pk_f16_f32 v16, v12, v13
	v_cvt_f32_f16_e32 v12, v134
	v_cvt_f32_f16_sdwa v13, v134 dst_sel:DWORD dst_unused:UNUSED_PAD src0_sel:WORD_1
	v_pk_fma_f32 v[8:9], v[8:9], v[96:97], v[12:13]
	s_nop 0
	v_cvt_pk_f16_f32 v18, v8, v9
	v_cvt_f32_f16_e32 v8, v133
	v_cvt_f32_f16_sdwa v9, v133 dst_sel:DWORD dst_unused:UNUSED_PAD src0_sel:WORD_1
	v_pk_fma_f32 v[8:9], v[14:15], v[102:103], v[8:9]
	s_nop 0
	v_cvt_pk_f16_f32 v17, v8, v9
	v_cvt_f32_f16_e32 v8, v135
	v_cvt_f32_f16_sdwa v9, v135 dst_sel:DWORD dst_unused:UNUSED_PAD src0_sel:WORD_1
	v_pk_fma_f32 v[8:9], v[10:11], v[98:99], v[8:9]
	s_nop 0
	v_cvt_pk_f16_f32 v19, v8, v9
	v_lshl_add_u64 v[8:9], s[0:1], 0, v[222:223]
	v_lshl_add_u64 v[12:13], v[8:9], 0, v[220:221]
	v_cvt_f32_f16_e32 v8, v120
	v_cvt_f32_f16_sdwa v9, v120 dst_sel:DWORD dst_unused:UNUSED_PAD src0_sel:WORD_1
	global_store_dwordx4 v[12:13], v[16:19], off
	v_pk_fma_f32 v[4:5], v[4:5], v[88:89], v[8:9]
	s_nop 0
	v_cvt_pk_f16_f32 v8, v4, v5
	v_cvt_f32_f16_e32 v4, v122
	v_cvt_f32_f16_sdwa v5, v122 dst_sel:DWORD dst_unused:UNUSED_PAD src0_sel:WORD_1
	v_pk_fma_f32 v[0:1], v[0:1], v[80:81], v[4:5]
	s_nop 0
	v_cvt_pk_f16_f32 v10, v0, v1
	v_cvt_f32_f16_e32 v0, v121
	v_cvt_f32_f16_sdwa v1, v121 dst_sel:DWORD dst_unused:UNUSED_PAD src0_sel:WORD_1
	v_pk_fma_f32 v[0:1], v[6:7], v[90:91], v[0:1]
	s_nop 0
	v_cvt_pk_f16_f32 v9, v0, v1
	v_cvt_f32_f16_e32 v0, v123
	v_cvt_f32_f16_sdwa v1, v123 dst_sel:DWORD dst_unused:UNUSED_PAD src0_sel:WORD_1
	v_pk_fma_f32 v[0:1], v[2:3], v[82:83], v[0:1]
	s_nop 0
	v_cvt_pk_f16_f32 v11, v0, v1
	global_store_dwordx4 v[12:13], v[8:11], off offset:256
	s_cbranch_vccz .LBB0_640
	s_waitcnt vmcnt(0)
	s_cmpk_gt_u32 s22, 0xff
	s_cbranch_scc1 .LBB0_651
	s_barrier

.LBB0_1185:
	ds_read_b128 v[88:91], v243
	ds_read_b128 v[96:99], v243 offset:1024
	ds_read_b128 v[108:111], v243 offset:2048
	ds_read_b128 v[116:119], v243 offset:3072
	s_add_u32 s26, s24, 0xfff80080
	s_addc_u32 s27, s25, -1
	s_cmp_eq_u32 s64, 28
	s_cselect_b32 s29, s17, s27
	s_cselect_b32 s28, s31, s26
	s_cselect_b32 s27, s15, s63
	s_cselect_b32 s26, s61, s62
	v_lshl_add_u64 v[176:177], s[24:25], 0, v[212:213]
	s_add_i32 m0, s23, 0xc000
	ds_read_b128 v[128:131], v244
	ds_read_b128 v[136:139], v244 offset:1024
	ds_read_b128 v[144:147], v244 offset:2048
	ds_read_b128 v[148:151], v244 offset:3072
	ds_read_b128 v[152:155], v244 offset:4096
	ds_read_b128 v[164:167], v244 offset:5120
	ds_read_b128 v[168:171], v244 offset:6144
	ds_read_b128 v[172:175], v244 offset:7168
	global_load_lds_dwordx4 v[176:177], off
	v_lshl_add_u64 v[176:177], s[24:25], 0, v[214:215]
	s_add_i32 m0, s23, 0xe000
	s_nop 0
	global_load_lds_dwordx4 v[176:177], off
	s_waitcnt lgkmcnt(8)
	s_barrier
	s_waitcnt lgkmcnt(0)
	s_setprio 1
	v_mfma_f32_16x16x32_f16 v[160:163], v[88:91], v[128:131], v[160:163]
	v_mfma_f32_16x16x32_f16 v[156:159], v[108:111], v[128:131], v[156:159]
	v_mfma_f32_16x16x32_f16 v[124:127], v[88:91], v[144:147], v[124:127]
	v_mfma_f32_16x16x32_f16 v[120:123], v[108:111], v[144:147], v[120:123]
	v_mfma_f32_16x16x32_f16 v[100:103], v[88:91], v[152:155], v[100:103]
	v_mfma_f32_16x16x32_f16 v[92:95], v[108:111], v[152:155], v[92:95]
	v_mfma_f32_16x16x32_f16 v[76:79], v[88:91], v[168:171], v[76:79]
	v_mfma_f32_16x16x32_f16 v[72:75], v[108:111], v[168:171], v[72:75]
	v_mfma_f32_16x16x32_f16 v[160:163], v[96:99], v[136:139], v[160:163]
	v_mfma_f32_16x16x32_f16 v[156:159], v[116:119], v[136:139], v[156:159]
	v_mfma_f32_16x16x32_f16 v[124:127], v[96:99], v[148:151], v[124:127]
	v_mfma_f32_16x16x32_f16 v[120:123], v[116:119], v[148:151], v[120:123]
	v_mfma_f32_16x16x32_f16 v[100:103], v[96:99], v[164:167], v[100:103]
	v_mfma_f32_16x16x32_f16 v[92:95], v[116:119], v[164:167], v[92:95]
	v_mfma_f32_16x16x32_f16 v[76:79], v[96:99], v[172:175], v[76:79]
	v_mfma_f32_16x16x32_f16 v[72:75], v[116:119], v[172:175], v[72:75]
	s_setprio 0
	s_barrier
	s_add_i32 s65, s59, s44
	v_lshl_add_u64 v[192:193], s[26:27], 0, v[206:207]
	s_mov_b32 m0, s65
	ds_read_b128 v[176:179], v245
	ds_read_b128 v[180:183], v245 offset:1024
	ds_read_b128 v[184:187], v245 offset:2048
	ds_read_b128 v[188:191], v245 offset:3072
	global_load_lds_dwordx4 v[192:193], off
	v_lshl_add_u64 v[194:195], s[26:27], 0, v[210:211]
	s_add_i32 m0, s65, 0x2000
	s_nop 0
	global_load_lds_dwordx4 v[194:195], off
	s_barrier
	s_waitcnt lgkmcnt(0)
	s_setprio 1
	v_mfma_f32_16x16x32_f16 v[140:143], v[176:179], v[128:131], v[140:143]
	v_mfma_f32_16x16x32_f16 v[112:115], v[176:179], v[144:147], v[112:115]
	v_mfma_f32_16x16x32_f16 v[104:107], v[184:187], v[144:147], v[104:107]
	v_mfma_f32_16x16x32_f16 v[84:87], v[176:179], v[152:155], v[84:87]
	v_mfma_f32_16x16x32_f16 v[80:83], v[184:187], v[152:155], v[80:83]
	v_mfma_f32_16x16x32_f16 v[68:71], v[176:179], v[168:171], v[68:71]
	v_mfma_f32_16x16x32_f16 v[64:67], v[184:187], v[168:171], v[64:67]
	v_mfma_f32_16x16x32_f16 v[140:143], v[180:183], v[136:139], v[140:143]
	v_mfma_f32_16x16x32_f16 v[128:131], v[184:187], v[128:131], v[132:135]
	v_mfma_f32_16x16x32_f16 v[112:115], v[180:183], v[148:151], v[112:115]
	v_mfma_f32_16x16x32_f16 v[104:107], v[188:191], v[148:151], v[104:107]
	v_mfma_f32_16x16x32_f16 v[84:87], v[180:183], v[164:167], v[84:87]
	v_mfma_f32_16x16x32_f16 v[80:83], v[188:191], v[164:167], v[80:83]
	v_mfma_f32_16x16x32_f16 v[68:71], v[180:183], v[172:175], v[68:71]
	v_mfma_f32_16x16x32_f16 v[64:67], v[188:191], v[172:175], v[64:67]
	v_mfma_f32_16x16x32_f16 v[128:131], v[188:191], v[136:139], v[128:131]
	s_setprio 0
	s_mov_b32 m0, s23
	v_lshl_add_u64 v[196:197], s[28:29], 0, v[204:205]
	s_barrier
	ds_read_b128 v[132:135], v244 offset:16384
	ds_read_b128 v[136:139], v244 offset:17408
	ds_read_b128 v[144:147], v244 offset:18432
	ds_read_b128 v[148:151], v244 offset:19456
	ds_read_b128 v[152:155], v244 offset:20480
	ds_read_b128 v[164:167], v244 offset:21504
	ds_read_b128 v[168:171], v244 offset:22528
	ds_read_b128 v[172:175], v244 offset:23552
	global_load_lds_dwordx4 v[196:197], off
	v_lshl_add_u64 v[198:199], s[28:29], 0, v[208:209]
	s_mov_b32 m0, s45
	s_nop 0
	global_load_lds_dwordx4 v[198:199], off
	s_barrier
	s_waitcnt lgkmcnt(0)
	s_setprio 1
	v_mfma_f32_16x16x32_f16 v[60:63], v[88:91], v[132:135], v[60:63]
	v_mfma_f32_16x16x32_f16 v[56:59], v[108:111], v[132:135], v[56:59]
	v_mfma_f32_16x16x32_f16 v[44:47], v[88:91], v[144:147], v[44:47]
	v_mfma_f32_16x16x32_f16 v[40:43], v[108:111], v[144:147], v[40:43]
	v_mfma_f32_16x16x32_f16 v[28:31], v[88:91], v[152:155], v[28:31]
	v_mfma_f32_16x16x32_f16 v[24:27], v[108:111], v[152:155], v[24:27]
	v_mfma_f32_16x16x32_f16 v[12:15], v[88:91], v[168:171], v[12:15]
	v_mfma_f32_16x16x32_f16 v[8:11], v[108:111], v[168:171], v[8:11]
	v_mfma_f32_16x16x32_f16 v[60:63], v[96:99], v[136:139], v[60:63]
	v_mfma_f32_16x16x32_f16 v[56:59], v[116:119], v[136:139], v[56:59]
	v_mfma_f32_16x16x32_f16 v[44:47], v[96:99], v[148:151], v[44:47]
	v_mfma_f32_16x16x32_f16 v[40:43], v[116:119], v[148:151], v[40:43]
	v_mfma_f32_16x16x32_f16 v[28:31], v[96:99], v[164:167], v[28:31]
	v_mfma_f32_16x16x32_f16 v[24:27], v[116:119], v[164:167], v[24:27]
	v_mfma_f32_16x16x32_f16 v[12:15], v[96:99], v[172:175], v[12:15]
	v_mfma_f32_16x16x32_f16 v[8:11], v[116:119], v[172:175], v[8:11]
	s_setprio 0
	s_barrier
	s_add_u32 s66, s26, 0x80000
	s_addc_u32 s67, s27, 0
	s_add_i32 s65, s60, s44
	v_lshl_add_u64 v[88:89], s[66:67], 0, v[206:207]
	s_mov_b32 m0, s65
	s_nop 0
	global_load_lds_dwordx4 v[88:89], off
	v_lshl_add_u64 v[88:89], s[66:67], 0, v[210:211]
	s_add_i32 m0, s65, 0x2000
	s_nop 0
	global_load_lds_dwordx4 v[88:89], off
	s_waitcnt vmcnt(6)
	s_barrier
	s_setprio 1
	v_mfma_f32_16x16x32_f16 v[52:55], v[176:179], v[132:135], v[52:55]
	v_mfma_f32_16x16x32_f16 v[48:51], v[184:187], v[132:135], v[48:51]
	v_mfma_f32_16x16x32_f16 v[36:39], v[176:179], v[144:147], v[36:39]
	v_mfma_f32_16x16x32_f16 v[32:35], v[184:187], v[144:147], v[32:35]
	v_mfma_f32_16x16x32_f16 v[20:23], v[176:179], v[152:155], v[20:23]
	v_mfma_f32_16x16x32_f16 v[16:19], v[184:187], v[152:155], v[16:19]
	v_mfma_f32_16x16x32_f16 v[4:7], v[176:179], v[168:171], v[4:7]
	v_mfma_f32_16x16x32_f16 v[0:3], v[184:187], v[168:171], v[0:3]
	v_mfma_f32_16x16x32_f16 v[52:55], v[180:183], v[136:139], v[52:55]
	v_mfma_f32_16x16x32_f16 v[48:51], v[188:191], v[136:139], v[48:51]
	v_mfma_f32_16x16x32_f16 v[36:39], v[180:183], v[148:151], v[36:39]
	v_mfma_f32_16x16x32_f16 v[32:35], v[188:191], v[148:151], v[32:35]
	v_mfma_f32_16x16x32_f16 v[20:23], v[180:183], v[164:167], v[20:23]
	v_mfma_f32_16x16x32_f16 v[16:19], v[188:191], v[164:167], v[16:19]
	v_mfma_f32_16x16x32_f16 v[4:7], v[180:183], v[172:175], v[4:7]
	v_mfma_f32_16x16x32_f16 v[0:3], v[188:191], v[172:175], v[0:3]
	s_setprio 0
	s_add_i32 s65, 0, 0x18000
	v_add_u32_e32 v116, s65, v241
	s_barrier
	ds_read_b128 v[88:91], v116
	ds_read_b128 v[96:99], v116 offset:1024
	ds_read_b128 v[108:111], v116 offset:2048
	ds_read_b128 v[116:119], v116 offset:3072
	s_add_u32 s28, s28, 0x80000
	s_addc_u32 s29, s29, 0
	s_mov_b32 m0, s48
	v_lshl_add_u64 v[176:177], s[28:29], 0, v[204:205]
	ds_read_b128 v[132:135], v244 offset:32768
	ds_read_b128 v[136:139], v244 offset:33792
	ds_read_b128 v[144:147], v244 offset:34816
	ds_read_b128 v[148:151], v244 offset:35840
	ds_read_b128 v[152:155], v244 offset:36864
	ds_read_b128 v[164:167], v244 offset:37888
	ds_read_b128 v[168:171], v244 offset:38912
	ds_read_b128 v[172:175], v244 offset:39936
	global_load_lds_dwordx4 v[176:177], off
	v_lshl_add_u64 v[176:177], s[28:29], 0, v[208:209]
	s_mov_b32 m0, s49
	s_nop 0
	global_load_lds_dwordx4 v[176:177], off
	s_waitcnt lgkmcnt(8)
	s_barrier
	s_waitcnt lgkmcnt(0)
	s_setprio 1
	v_mfma_f32_16x16x32_f16 v[160:163], v[88:91], v[132:135], v[160:163]
	v_mfma_f32_16x16x32_f16 v[156:159], v[108:111], v[132:135], v[156:159]
	v_mfma_f32_16x16x32_f16 v[124:127], v[88:91], v[144:147], v[124:127]
	v_mfma_f32_16x16x32_f16 v[120:123], v[108:111], v[144:147], v[120:123]
	v_mfma_f32_16x16x32_f16 v[100:103], v[88:91], v[152:155], v[100:103]
	v_mfma_f32_16x16x32_f16 v[92:95], v[108:111], v[152:155], v[92:95]
	v_mfma_f32_16x16x32_f16 v[76:79], v[88:91], v[168:171], v[76:79]
	v_mfma_f32_16x16x32_f16 v[72:75], v[108:111], v[168:171], v[72:75]
	v_mfma_f32_16x16x32_f16 v[160:163], v[96:99], v[136:139], v[160:163]
	v_mfma_f32_16x16x32_f16 v[156:159], v[116:119], v[136:139], v[156:159]
	v_mfma_f32_16x16x32_f16 v[124:127], v[96:99], v[148:151], v[124:127]
	v_mfma_f32_16x16x32_f16 v[120:123], v[116:119], v[148:151], v[120:123]
	v_mfma_f32_16x16x32_f16 v[100:103], v[96:99], v[164:167], v[100:103]
	v_mfma_f32_16x16x32_f16 v[92:95], v[116:119], v[164:167], v[92:95]
	v_mfma_f32_16x16x32_f16 v[76:79], v[96:99], v[172:175], v[76:79]
	v_mfma_f32_16x16x32_f16 v[72:75], v[116:119], v[172:175], v[72:75]
	s_setprio 0
	s_barrier
	s_add_i32 s28, 0, 0x1c000
	s_add_i32 s29, s65, s44
	v_add_u32_e32 v188, s28, v241
	v_lshl_add_u64 v[192:193], v[192:193], 0, s[6:7]
	s_mov_b32 m0, s29
	ds_read_b128 v[176:179], v188
	ds_read_b128 v[180:183], v188 offset:1024
	ds_read_b128 v[184:187], v188 offset:2048
	ds_read_b128 v[188:191], v188 offset:3072
	global_load_lds_dwordx4 v[192:193], off
	v_lshl_add_u64 v[192:193], v[194:195], 0, s[6:7]
	s_add_i32 m0, s29, 0x2000
	s_nop 0
	global_load_lds_dwordx4 v[192:193], off
	s_barrier
	s_waitcnt lgkmcnt(0)
	s_setprio 1
	v_mfma_f32_16x16x32_f16 v[140:143], v[176:179], v[132:135], v[140:143]
	v_mfma_f32_16x16x32_f16 v[128:131], v[184:187], v[132:135], v[128:131]
	v_mfma_f32_16x16x32_f16 v[112:115], v[176:179], v[144:147], v[112:115]
	v_mfma_f32_16x16x32_f16 v[104:107], v[184:187], v[144:147], v[104:107]
	v_mfma_f32_16x16x32_f16 v[84:87], v[176:179], v[152:155], v[84:87]
	v_mfma_f32_16x16x32_f16 v[80:83], v[184:187], v[152:155], v[80:83]
	v_mfma_f32_16x16x32_f16 v[68:71], v[176:179], v[168:171], v[68:71]
	v_mfma_f32_16x16x32_f16 v[64:67], v[184:187], v[168:171], v[64:67]
	v_mfma_f32_16x16x32_f16 v[140:143], v[180:183], v[136:139], v[140:143]
	v_mfma_f32_16x16x32_f16 v[132:135], v[188:191], v[136:139], v[128:131]
	v_mfma_f32_16x16x32_f16 v[112:115], v[180:183], v[148:151], v[112:115]
	v_mfma_f32_16x16x32_f16 v[104:107], v[188:191], v[148:151], v[104:107]
	v_mfma_f32_16x16x32_f16 v[84:87], v[180:183], v[164:167], v[84:87]
	v_mfma_f32_16x16x32_f16 v[80:83], v[188:191], v[164:167], v[80:83]
	v_mfma_f32_16x16x32_f16 v[68:71], v[180:183], v[172:175], v[68:71]
	v_mfma_f32_16x16x32_f16 v[64:67], v[188:191], v[172:175], v[64:67]
	s_setprio 0
	s_mov_b32 m0, s51
	v_lshl_add_u64 v[192:193], v[196:197], 0, s[6:7]
	s_barrier
	ds_read_b128 v[128:131], v244 offset:49152
	ds_read_b128 v[136:139], v244 offset:50176
	ds_read_b128 v[144:147], v244 offset:51200
	ds_read_b128 v[148:151], v244 offset:52224
	ds_read_b128 v[152:155], v244 offset:53248
	ds_read_b128 v[164:167], v244 offset:54272
	ds_read_b128 v[168:171], v244 offset:55296
	ds_read_b128 v[172:175], v244 offset:56320
	global_load_lds_dwordx4 v[192:193], off
	v_lshl_add_u64 v[192:193], v[198:199], 0, s[6:7]
	s_mov_b32 m0, s54
	s_nop 0
	global_load_lds_dwordx4 v[192:193], off
	s_barrier
	s_waitcnt lgkmcnt(0)
	s_setprio 1
	v_mfma_f32_16x16x32_f16 v[60:63], v[88:91], v[128:131], v[60:63]
	v_mfma_f32_16x16x32_f16 v[56:59], v[108:111], v[128:131], v[56:59]
	v_mfma_f32_16x16x32_f16 v[44:47], v[88:91], v[144:147], v[44:47]
	v_mfma_f32_16x16x32_f16 v[40:43], v[108:111], v[144:147], v[40:43]
	v_mfma_f32_16x16x32_f16 v[28:31], v[88:91], v[152:155], v[28:31]
	v_mfma_f32_16x16x32_f16 v[24:27], v[108:111], v[152:155], v[24:27]
	v_mfma_f32_16x16x32_f16 v[12:15], v[88:91], v[168:171], v[12:15]
	v_mfma_f32_16x16x32_f16 v[8:11], v[108:111], v[168:171], v[8:11]
	v_mfma_f32_16x16x32_f16 v[60:63], v[96:99], v[136:139], v[60:63]
	v_mfma_f32_16x16x32_f16 v[56:59], v[116:119], v[136:139], v[56:59]
	v_mfma_f32_16x16x32_f16 v[44:47], v[96:99], v[148:151], v[44:47]
	v_mfma_f32_16x16x32_f16 v[40:43], v[116:119], v[148:151], v[40:43]
	v_mfma_f32_16x16x32_f16 v[28:31], v[96:99], v[164:167], v[28:31]
	v_mfma_f32_16x16x32_f16 v[24:27], v[116:119], v[164:167], v[24:27]
	v_mfma_f32_16x16x32_f16 v[12:15], v[96:99], v[172:175], v[12:15]
	v_mfma_f32_16x16x32_f16 v[8:11], v[116:119], v[172:175], v[8:11]
	s_setprio 0
	s_barrier
	s_add_u32 s26, s26, 0x80080
	s_addc_u32 s27, s27, 0
	s_add_i32 s28, s28, s44
	v_lshl_add_u64 v[88:89], s[26:27], 0, v[206:207]
	s_mov_b32 m0, s28
	s_nop 0
	global_load_lds_dwordx4 v[88:89], off
	v_lshl_add_u64 v[88:89], s[26:27], 0, v[210:211]
	s_add_i32 m0, s28, 0x2000
	s_nop 0
	global_load_lds_dwordx4 v[88:89], off
	s_waitcnt vmcnt(6)
	s_barrier
	s_setprio 1
	v_mfma_f32_16x16x32_f16 v[52:55], v[176:179], v[128:131], v[52:55]
	v_mfma_f32_16x16x32_f16 v[48:51], v[184:187], v[128:131], v[48:51]
	v_mfma_f32_16x16x32_f16 v[36:39], v[176:179], v[144:147], v[36:39]
	v_mfma_f32_16x16x32_f16 v[32:35], v[184:187], v[144:147], v[32:35]
	v_mfma_f32_16x16x32_f16 v[20:23], v[176:179], v[152:155], v[20:23]
	v_mfma_f32_16x16x32_f16 v[16:19], v[184:187], v[152:155], v[16:19]
	v_mfma_f32_16x16x32_f16 v[4:7], v[176:179], v[168:171], v[4:7]
	v_mfma_f32_16x16x32_f16 v[0:3], v[184:187], v[168:171], v[0:3]
	v_mfma_f32_16x16x32_f16 v[52:55], v[180:183], v[136:139], v[52:55]
	v_mfma_f32_16x16x32_f16 v[48:51], v[188:191], v[136:139], v[48:51]
	v_mfma_f32_16x16x32_f16 v[36:39], v[180:183], v[148:151], v[36:39]
	v_mfma_f32_16x16x32_f16 v[32:35], v[188:191], v[148:151], v[32:35]
	v_mfma_f32_16x16x32_f16 v[20:23], v[180:183], v[164:167], v[20:23]
	v_mfma_f32_16x16x32_f16 v[16:19], v[188:191], v[164:167], v[16:19]
	v_mfma_f32_16x16x32_f16 v[4:7], v[180:183], v[172:175], v[4:7]
	v_mfma_f32_16x16x32_f16 v[0:3], v[188:191], v[172:175], v[0:3]
	s_setprio 0
	s_add_i32 s64, s64, 2
	s_add_u32 s24, s24, 0x100
	s_addc_u32 s25, s25, 0
	s_add_u32 s62, s62, 0x100
	s_addc_u32 s63, s63, 0
	s_cmp_gt_u32 s64, 29
	s_barrier
	s_cbranch_scc0 .LBB0_1185
	s_lshl_b32 s15, s22, 8
	s_add_i32 s17, s15, 0xffffe000
	s_lshr_b32 s17, s17, 11
	s_mulk_i32 s17, 0x1800
	s_addk_i32 s17, 0x1800
	s_cmp_gt_i32 s22, 31
	s_cselect_b32 s24, s17, 0
	s_ashr_i32 s25, s24, 31
	v_lshl_or_b32 v128, s30, 8, v242
	s_lshl_b64 s[24:25], s[24:25], 2
	s_add_u32 s24, s42, s24
	v_ashrrev_i32_e32 v129, 31, v128
	v_add_u32_e32 v130, s15, v240
	s_addc_u32 s25, s43, s25
	v_lshlrev_b64 v[220:221], 1, v[128:129]
	v_ashrrev_i32_e32 v131, 31, v130
	v_lshl_add_u64 v[96:97], v[128:129], 2, s[24:25]
	v_lshl_add_u64 v[128:129], s[4:5], 0, v[220:221]
	v_lshlrev_b64 v[236:237], 12, v[130:131]
	v_lshl_add_u64 v[136:137], v[128:129], 0, v[236:237]
	global_load_dwordx4 v[108:111], v[96:97], off offset:16
	global_load_dwordx4 v[116:119], v[96:97], off
	global_load_dwordx4 v[88:91], v[96:97], off offset:528
	s_nop 0
	global_load_dwordx4 v[96:99], v[96:97], off offset:512
	s_nop 0
	global_load_dwordx4 v[246:249], v[136:137], off nt
	global_load_dwordx4 v[200:203], v[136:137], off offset:256 nt
	v_or_b32_e32 v136, 16, v130
	v_ashrrev_i32_e32 v137, 31, v136
	v_lshlrev_b64 v[234:235], 12, v[136:137]
	v_lshl_add_u64 v[136:137], v[128:129], 0, v[234:235]
	global_load_dwordx4 v[196:199], v[136:137], off nt
	global_load_dwordx4 v[192:195], v[136:137], off offset:256 nt
	v_or_b32_e32 v136, 32, v130
	v_ashrrev_i32_e32 v137, 31, v136
	v_lshlrev_b64 v[232:233], 12, v[136:137]
	v_lshl_add_u64 v[136:137], v[128:129], 0, v[232:233]
	global_load_dwordx4 v[188:191], v[136:137], off nt
	global_load_dwordx4 v[184:187], v[136:137], off offset:256 nt
	v_readlane_b32 s64, v254, 21
	v_readlane_b32 s68, v254, 25
	v_readlane_b32 s69, v254, 26
	s_mov_b64 s[56:57], s[68:69]
	v_or_b32_e32 v130, 48, v130
	v_ashrrev_i32_e32 v131, 31, v130
	v_lshlrev_b64 v[230:231], 12, v[130:131]
	v_lshl_add_u64 v[130:131], v[128:129], 0, v[230:231]
	global_load_dwordx4 v[180:183], v[130:131], off nt
	global_load_dwordx4 v[176:179], v[130:131], off offset:256 nt
	v_lshl_add_u64 v[228:229], v[236:237], 0, s[0:1]
	v_lshl_add_u64 v[130:131], v[128:129], 0, v[228:229]
	global_load_dwordx4 v[172:175], v[130:131], off nt
	global_load_dwordx4 v[168:171], v[130:131], off offset:256 nt
	v_lshl_add_u64 v[226:227], v[236:237], 0, s[8:9]
	v_lshl_add_u64 v[130:131], v[128:129], 0, v[226:227]
	global_load_dwordx4 v[164:167], v[130:131], off nt
	global_load_dwordx4 v[152:155], v[130:131], off offset:256 nt
	v_lshl_add_u64 v[224:225], v[236:237], 0, s[10:11]
	v_lshl_add_u64 v[130:131], v[128:129], 0, v[224:225]
	global_load_dwordx4 v[148:151], v[130:131], off nt
	global_load_dwordx4 v[144:147], v[130:131], off offset:256 nt
	v_lshl_add_u64 v[222:223], v[236:237], 0, s[12:13]
	v_lshl_add_u64 v[128:129], v[128:129], 0, v[222:223]
	global_load_dwordx4 v[136:139], v[128:129], off nt
	s_nop 0
	global_load_dwordx4 v[128:131], v[128:129], off offset:256 nt
	s_and_b64 vcc, exec, s[2:3]
	s_mov_b32 s30, s14
	s_mov_b32 s22, s16
	s_mov_b64 s[26:27], s[20:21]
	s_mov_b64 s[24:25], s[18:19]
	v_readlane_b32 s65, v254, 22
	v_readlane_b32 s66, v254, 23
	v_readlane_b32 s67, v254, 24
	v_readlane_b32 s70, v254, 27
	v_readlane_b32 s71, v254, 28
	v_readlane_b32 s72, v254, 29
	v_readlane_b32 s73, v254, 30
	v_readlane_b32 s74, v254, 31
	v_readlane_b32 s75, v254, 32
	v_readlane_b32 s76, v254, 33
	v_readlane_b32 s77, v254, 34
	v_readlane_b32 s78, v254, 35
	v_readlane_b32 s79, v254, 36
	s_waitcnt vmcnt(0)
	v_cvt_f32_f16_e32 v250, v246
	v_cvt_f32_f16_sdwa v251, v246 dst_sel:DWORD dst_unused:UNUSED_PAD src0_sel:WORD_1
	v_pk_fma_f32 v[160:161], v[160:161], v[116:117], v[250:251]
	s_nop 0
	v_cvt_pk_f16_f32 v246, v160, v161
	v_cvt_f32_f16_e32 v160, v248
	v_cvt_f32_f16_sdwa v161, v248 dst_sel:DWORD dst_unused:UNUSED_PAD src0_sel:WORD_1
	v_pk_fma_f32 v[156:157], v[156:157], v[108:109], v[160:161]
	s_nop 0
	v_cvt_pk_f16_f32 v248, v156, v157
	v_cvt_f32_f16_e32 v156, v247
	v_cvt_f32_f16_sdwa v157, v247 dst_sel:DWORD dst_unused:UNUSED_PAD src0_sel:WORD_1
	v_pk_fma_f32 v[156:157], v[162:163], v[118:119], v[156:157]
	s_nop 0
	v_cvt_pk_f16_f32 v247, v156, v157
	v_cvt_f32_f16_e32 v156, v249
	v_cvt_f32_f16_sdwa v157, v249 dst_sel:DWORD dst_unused:UNUSED_PAD src0_sel:WORD_1
	v_pk_fma_f32 v[156:157], v[158:159], v[110:111], v[156:157]
	s_nop 0
	v_cvt_pk_f16_f32 v249, v156, v157
	v_lshl_add_u64 v[156:157], s[56:57], 0, v[236:237]
	v_lshl_add_u64 v[160:161], v[156:157], 0, v[220:221]
	v_cvt_f32_f16_e32 v156, v200
	v_cvt_f32_f16_sdwa v157, v200 dst_sel:DWORD dst_unused:UNUSED_PAD src0_sel:WORD_1
	global_store_dwordx4 v[160:161], v[246:249], off
	v_pk_fma_f32 v[140:141], v[140:141], v[96:97], v[156:157]
	s_nop 0
	v_cvt_pk_f16_f32 v156, v140, v141
	v_cvt_f32_f16_e32 v140, v202
	v_cvt_f32_f16_sdwa v141, v202 dst_sel:DWORD dst_unused:UNUSED_PAD src0_sel:WORD_1
	v_pk_fma_f32 v[132:133], v[132:133], v[88:89], v[140:141]
	s_nop 0
	v_cvt_pk_f16_f32 v158, v132, v133
	v_cvt_f32_f16_e32 v132, v201
	v_cvt_f32_f16_sdwa v133, v201 dst_sel:DWORD dst_unused:UNUSED_PAD src0_sel:WORD_1
	v_pk_fma_f32 v[132:133], v[142:143], v[98:99], v[132:133]
	s_nop 0
	v_cvt_pk_f16_f32 v157, v132, v133
	v_cvt_f32_f16_e32 v132, v203
	v_cvt_f32_f16_sdwa v133, v203 dst_sel:DWORD dst_unused:UNUSED_PAD src0_sel:WORD_1
	v_pk_fma_f32 v[132:133], v[134:135], v[90:91], v[132:133]
	s_nop 0
	v_cvt_pk_f16_f32 v159, v132, v133
	v_cvt_f32_f16_e32 v132, v196
	v_cvt_f32_f16_sdwa v133, v196 dst_sel:DWORD dst_unused:UNUSED_PAD src0_sel:WORD_1
	global_store_dwordx4 v[160:161], v[156:159], off offset:256
	v_pk_fma_f32 v[124:125], v[124:125], v[116:117], v[132:133]
	s_nop 0
	v_cvt_pk_f16_f32 v132, v124, v125
	v_cvt_f32_f16_e32 v124, v198
	v_cvt_f32_f16_sdwa v125, v198 dst_sel:DWORD dst_unused:UNUSED_PAD src0_sel:WORD_1
	v_pk_fma_f32 v[120:121], v[120:121], v[108:109], v[124:125]
	s_nop 0
	v_cvt_pk_f16_f32 v134, v120, v121
	v_cvt_f32_f16_e32 v120, v197
	v_cvt_f32_f16_sdwa v121, v197 dst_sel:DWORD dst_unused:UNUSED_PAD src0_sel:WORD_1
	v_pk_fma_f32 v[120:121], v[126:127], v[118:119], v[120:121]
	s_nop 0
	v_cvt_pk_f16_f32 v133, v120, v121
	v_cvt_f32_f16_e32 v120, v199
	v_cvt_f32_f16_sdwa v121, v199 dst_sel:DWORD dst_unused:UNUSED_PAD src0_sel:WORD_1
	v_pk_fma_f32 v[120:121], v[122:123], v[110:111], v[120:121]
	s_nop 0
	v_cvt_pk_f16_f32 v135, v120, v121
	v_lshl_add_u64 v[120:121], s[56:57], 0, v[234:235]
	v_lshl_add_u64 v[124:125], v[120:121], 0, v[220:221]
	v_cvt_f32_f16_e32 v120, v192
	v_cvt_f32_f16_sdwa v121, v192 dst_sel:DWORD dst_unused:UNUSED_PAD src0_sel:WORD_1
	global_store_dwordx4 v[124:125], v[132:135], off
	v_pk_fma_f32 v[112:113], v[112:113], v[96:97], v[120:121]
	s_nop 0
	v_cvt_pk_f16_f32 v120, v112, v113
	v_cvt_f32_f16_e32 v112, v194
	v_cvt_f32_f16_sdwa v113, v194 dst_sel:DWORD dst_unused:UNUSED_PAD src0_sel:WORD_1
	v_pk_fma_f32 v[104:105], v[104:105], v[88:89], v[112:113]
	s_nop 0
	v_cvt_pk_f16_f32 v122, v104, v105
	v_cvt_f32_f16_e32 v104, v193
	v_cvt_f32_f16_sdwa v105, v193 dst_sel:DWORD dst_unused:UNUSED_PAD src0_sel:WORD_1
	v_pk_fma_f32 v[104:105], v[114:115], v[98:99], v[104:105]
	s_nop 0
	v_cvt_pk_f16_f32 v121, v104, v105
	v_cvt_f32_f16_e32 v104, v195
	v_cvt_f32_f16_sdwa v105, v195 dst_sel:DWORD dst_unused:UNUSED_PAD src0_sel:WORD_1
	v_pk_fma_f32 v[104:105], v[106:107], v[90:91], v[104:105]
	s_nop 0
	v_cvt_pk_f16_f32 v123, v104, v105
	v_cvt_f32_f16_e32 v104, v188
	v_cvt_f32_f16_sdwa v105, v188 dst_sel:DWORD dst_unused:UNUSED_PAD src0_sel:WORD_1
	global_store_dwordx4 v[124:125], v[120:123], off offset:256
	v_pk_fma_f32 v[100:101], v[100:101], v[116:117], v[104:105]
	s_nop 0
	v_cvt_pk_f16_f32 v104, v100, v101
	v_cvt_f32_f16_e32 v100, v190
	v_cvt_f32_f16_sdwa v101, v190 dst_sel:DWORD dst_unused:UNUSED_PAD src0_sel:WORD_1
	v_pk_fma_f32 v[92:93], v[92:93], v[108:109], v[100:101]
	s_nop 0
	v_cvt_pk_f16_f32 v106, v92, v93
	v_cvt_f32_f16_e32 v92, v189
	v_cvt_f32_f16_sdwa v93, v189 dst_sel:DWORD dst_unused:UNUSED_PAD src0_sel:WORD_1
	v_pk_fma_f32 v[92:93], v[102:103], v[118:119], v[92:93]
	s_nop 0
	v_cvt_pk_f16_f32 v105, v92, v93
	v_cvt_f32_f16_e32 v92, v191
	v_cvt_f32_f16_sdwa v93, v191 dst_sel:DWORD dst_unused:UNUSED_PAD src0_sel:WORD_1
	v_pk_fma_f32 v[92:93], v[94:95], v[110:111], v[92:93]
	s_nop 0
	v_cvt_pk_f16_f32 v107, v92, v93
	v_lshl_add_u64 v[92:93], s[56:57], 0, v[232:233]
	v_lshl_add_u64 v[100:101], v[92:93], 0, v[220:221]
	v_cvt_f32_f16_e32 v92, v184
	v_cvt_f32_f16_sdwa v93, v184 dst_sel:DWORD dst_unused:UNUSED_PAD src0_sel:WORD_1
	global_store_dwordx4 v[100:101], v[104:107], off
	v_pk_fma_f32 v[84:85], v[84:85], v[96:97], v[92:93]
	s_nop 0
	v_cvt_pk_f16_f32 v92, v84, v85
	v_cvt_f32_f16_e32 v84, v186
	v_cvt_f32_f16_sdwa v85, v186 dst_sel:DWORD dst_unused:UNUSED_PAD src0_sel:WORD_1
	v_pk_fma_f32 v[80:81], v[80:81], v[88:89], v[84:85]
	s_nop 0
	v_cvt_pk_f16_f32 v94, v80, v81
	v_cvt_f32_f16_e32 v80, v185
	v_cvt_f32_f16_sdwa v81, v185 dst_sel:DWORD dst_unused:UNUSED_PAD src0_sel:WORD_1
	v_pk_fma_f32 v[80:81], v[86:87], v[98:99], v[80:81]
	s_nop 0
	v_cvt_pk_f16_f32 v93, v80, v81
	v_cvt_f32_f16_e32 v80, v187
	v_cvt_f32_f16_sdwa v81, v187 dst_sel:DWORD dst_unused:UNUSED_PAD src0_sel:WORD_1
	v_pk_fma_f32 v[80:81], v[82:83], v[90:91], v[80:81]
	s_nop 0
	v_cvt_pk_f16_f32 v95, v80, v81
	v_cvt_f32_f16_e32 v80, v180
	v_cvt_f32_f16_sdwa v81, v180 dst_sel:DWORD dst_unused:UNUSED_PAD src0_sel:WORD_1
	global_store_dwordx4 v[100:101], v[92:95], off offset:256
	v_pk_fma_f32 v[76:77], v[76:77], v[116:117], v[80:81]
	s_nop 0
	v_cvt_pk_f16_f32 v80, v76, v77
	v_cvt_f32_f16_e32 v76, v182
	v_cvt_f32_f16_sdwa v77, v182 dst_sel:DWORD dst_unused:UNUSED_PAD src0_sel:WORD_1
	v_pk_fma_f32 v[72:73], v[72:73], v[108:109], v[76:77]
	s_nop 0
	v_cvt_pk_f16_f32 v82, v72, v73
	v_cvt_f32_f16_e32 v72, v181
	v_cvt_f32_f16_sdwa v73, v181 dst_sel:DWORD dst_unused:UNUSED_PAD src0_sel:WORD_1
	v_pk_fma_f32 v[72:73], v[78:79], v[118:119], v[72:73]
	s_nop 0
	v_cvt_pk_f16_f32 v81, v72, v73
	v_cvt_f32_f16_e32 v72, v183
	v_cvt_f32_f16_sdwa v73, v183 dst_sel:DWORD dst_unused:UNUSED_PAD src0_sel:WORD_1
	v_pk_fma_f32 v[72:73], v[74:75], v[110:111], v[72:73]
	s_nop 0
	v_cvt_pk_f16_f32 v83, v72, v73
	v_lshl_add_u64 v[72:73], s[56:57], 0, v[230:231]
	v_lshl_add_u64 v[76:77], v[72:73], 0, v[220:221]
	v_cvt_f32_f16_e32 v72, v176
	v_cvt_f32_f16_sdwa v73, v176 dst_sel:DWORD dst_unused:UNUSED_PAD src0_sel:WORD_1
	global_store_dwordx4 v[76:77], v[80:83], off
	v_pk_fma_f32 v[68:69], v[68:69], v[96:97], v[72:73]
	s_nop 0
	v_cvt_pk_f16_f32 v72, v68, v69
	v_cvt_f32_f16_e32 v68, v178
	v_cvt_f32_f16_sdwa v69, v178 dst_sel:DWORD dst_unused:UNUSED_PAD src0_sel:WORD_1
	v_pk_fma_f32 v[64:65], v[64:65], v[88:89], v[68:69]
	s_nop 0
	v_cvt_pk_f16_f32 v74, v64, v65
	v_cvt_f32_f16_e32 v64, v177
	v_cvt_f32_f16_sdwa v65, v177 dst_sel:DWORD dst_unused:UNUSED_PAD src0_sel:WORD_1
	v_pk_fma_f32 v[64:65], v[70:71], v[98:99], v[64:65]
	s_nop 0
	v_cvt_pk_f16_f32 v73, v64, v65
	v_cvt_f32_f16_e32 v64, v179
	v_cvt_f32_f16_sdwa v65, v179 dst_sel:DWORD dst_unused:UNUSED_PAD src0_sel:WORD_1
	v_pk_fma_f32 v[64:65], v[66:67], v[90:91], v[64:65]
	s_nop 0
	v_cvt_pk_f16_f32 v75, v64, v65
	v_cvt_f32_f16_e32 v64, v172
	v_cvt_f32_f16_sdwa v65, v172 dst_sel:DWORD dst_unused:UNUSED_PAD src0_sel:WORD_1
	global_store_dwordx4 v[76:77], v[72:75], off offset:256
	v_pk_fma_f32 v[60:61], v[60:61], v[116:117], v[64:65]
	s_nop 0
	v_cvt_pk_f16_f32 v64, v60, v61
	v_cvt_f32_f16_e32 v60, v174
	v_cvt_f32_f16_sdwa v61, v174 dst_sel:DWORD dst_unused:UNUSED_PAD src0_sel:WORD_1
	v_pk_fma_f32 v[56:57], v[56:57], v[108:109], v[60:61]
	s_nop 0
	v_cvt_pk_f16_f32 v66, v56, v57
	v_cvt_f32_f16_e32 v56, v173
	v_cvt_f32_f16_sdwa v57, v173 dst_sel:DWORD dst_unused:UNUSED_PAD src0_sel:WORD_1
	v_pk_fma_f32 v[56:57], v[62:63], v[118:119], v[56:57]
	s_nop 0
	v_cvt_pk_f16_f32 v65, v56, v57
	v_cvt_f32_f16_e32 v56, v175
	v_cvt_f32_f16_sdwa v57, v175 dst_sel:DWORD dst_unused:UNUSED_PAD src0_sel:WORD_1
	v_pk_fma_f32 v[56:57], v[58:59], v[110:111], v[56:57]
	s_nop 0
	v_cvt_pk_f16_f32 v67, v56, v57
	v_lshl_add_u64 v[56:57], s[56:57], 0, v[228:229]
	v_lshl_add_u64 v[60:61], v[56:57], 0, v[220:221]
	v_cvt_f32_f16_e32 v56, v168
	v_cvt_f32_f16_sdwa v57, v168 dst_sel:DWORD dst_unused:UNUSED_PAD src0_sel:WORD_1
	global_store_dwordx4 v[60:61], v[64:67], off
	v_pk_fma_f32 v[52:53], v[52:53], v[96:97], v[56:57]
	s_nop 0
	v_cvt_pk_f16_f32 v56, v52, v53
	v_cvt_f32_f16_e32 v52, v170
	v_cvt_f32_f16_sdwa v53, v170 dst_sel:DWORD dst_unused:UNUSED_PAD src0_sel:WORD_1
	v_pk_fma_f32 v[48:49], v[48:49], v[88:89], v[52:53]
	s_nop 0
	v_cvt_pk_f16_f32 v58, v48, v49
	v_cvt_f32_f16_e32 v48, v169
	v_cvt_f32_f16_sdwa v49, v169 dst_sel:DWORD dst_unused:UNUSED_PAD src0_sel:WORD_1
	v_pk_fma_f32 v[48:49], v[54:55], v[98:99], v[48:49]
	s_nop 0
	v_cvt_pk_f16_f32 v57, v48, v49
	v_cvt_f32_f16_e32 v48, v171
	v_cvt_f32_f16_sdwa v49, v171 dst_sel:DWORD dst_unused:UNUSED_PAD src0_sel:WORD_1
	v_pk_fma_f32 v[48:49], v[50:51], v[90:91], v[48:49]
	s_nop 0
	v_cvt_pk_f16_f32 v59, v48, v49
	v_cvt_f32_f16_e32 v48, v164
	v_cvt_f32_f16_sdwa v49, v164 dst_sel:DWORD dst_unused:UNUSED_PAD src0_sel:WORD_1
	global_store_dwordx4 v[60:61], v[56:59], off offset:256
	v_pk_fma_f32 v[44:45], v[44:45], v[116:117], v[48:49]
	s_nop 0
	v_cvt_pk_f16_f32 v48, v44, v45
	v_cvt_f32_f16_e32 v44, v166
	v_cvt_f32_f16_sdwa v45, v166 dst_sel:DWORD dst_unused:UNUSED_PAD src0_sel:WORD_1
	v_pk_fma_f32 v[40:41], v[40:41], v[108:109], v[44:45]
	s_nop 0
	v_cvt_pk_f16_f32 v50, v40, v41
	v_cvt_f32_f16_e32 v40, v165
	v_cvt_f32_f16_sdwa v41, v165 dst_sel:DWORD dst_unused:UNUSED_PAD src0_sel:WORD_1
	v_pk_fma_f32 v[40:41], v[46:47], v[118:119], v[40:41]
	s_nop 0
	v_cvt_pk_f16_f32 v49, v40, v41
	v_cvt_f32_f16_e32 v40, v167
	v_cvt_f32_f16_sdwa v41, v167 dst_sel:DWORD dst_unused:UNUSED_PAD src0_sel:WORD_1
	v_pk_fma_f32 v[40:41], v[42:43], v[110:111], v[40:41]
	s_nop 0
	v_cvt_pk_f16_f32 v51, v40, v41
	v_lshl_add_u64 v[40:41], s[56:57], 0, v[226:227]
	v_lshl_add_u64 v[44:45], v[40:41], 0, v[220:221]
	v_cvt_f32_f16_e32 v40, v152
	v_cvt_f32_f16_sdwa v41, v152 dst_sel:DWORD dst_unused:UNUSED_PAD src0_sel:WORD_1
	global_store_dwordx4 v[44:45], v[48:51], off
	v_pk_fma_f32 v[36:37], v[36:37], v[96:97], v[40:41]
	s_nop 0
	v_cvt_pk_f16_f32 v40, v36, v37
	v_cvt_f32_f16_e32 v36, v154
	v_cvt_f32_f16_sdwa v37, v154 dst_sel:DWORD dst_unused:UNUSED_PAD src0_sel:WORD_1
	v_pk_fma_f32 v[32:33], v[32:33], v[88:89], v[36:37]
	s_nop 0
	v_cvt_pk_f16_f32 v42, v32, v33
	v_cvt_f32_f16_e32 v32, v153
	v_cvt_f32_f16_sdwa v33, v153 dst_sel:DWORD dst_unused:UNUSED_PAD src0_sel:WORD_1
	v_pk_fma_f32 v[32:33], v[38:39], v[98:99], v[32:33]
	s_nop 0
	v_cvt_pk_f16_f32 v41, v32, v33
	v_cvt_f32_f16_e32 v32, v155
	v_cvt_f32_f16_sdwa v33, v155 dst_sel:DWORD dst_unused:UNUSED_PAD src0_sel:WORD_1
	v_pk_fma_f32 v[32:33], v[34:35], v[90:91], v[32:33]
	s_nop 0
	v_cvt_pk_f16_f32 v43, v32, v33
	v_cvt_f32_f16_e32 v32, v148
	v_cvt_f32_f16_sdwa v33, v148 dst_sel:DWORD dst_unused:UNUSED_PAD src0_sel:WORD_1
	global_store_dwordx4 v[44:45], v[40:43], off offset:256
	v_pk_fma_f32 v[28:29], v[28:29], v[116:117], v[32:33]
	s_nop 0
	v_cvt_pk_f16_f32 v32, v28, v29
	v_cvt_f32_f16_e32 v28, v150
	v_cvt_f32_f16_sdwa v29, v150 dst_sel:DWORD dst_unused:UNUSED_PAD src0_sel:WORD_1
	v_pk_fma_f32 v[24:25], v[24:25], v[108:109], v[28:29]
	s_nop 0
	v_cvt_pk_f16_f32 v34, v24, v25
	v_cvt_f32_f16_e32 v24, v149
	v_cvt_f32_f16_sdwa v25, v149 dst_sel:DWORD dst_unused:UNUSED_PAD src0_sel:WORD_1
	v_pk_fma_f32 v[24:25], v[30:31], v[118:119], v[24:25]
	s_nop 0
	v_cvt_pk_f16_f32 v33, v24, v25
	v_cvt_f32_f16_e32 v24, v151
	v_cvt_f32_f16_sdwa v25, v151 dst_sel:DWORD dst_unused:UNUSED_PAD src0_sel:WORD_1
	v_pk_fma_f32 v[24:25], v[26:27], v[110:111], v[24:25]
	s_nop 0
	v_cvt_pk_f16_f32 v35, v24, v25
	v_lshl_add_u64 v[24:25], s[56:57], 0, v[224:225]
	v_lshl_add_u64 v[28:29], v[24:25], 0, v[220:221]
	v_cvt_f32_f16_e32 v24, v144
	v_cvt_f32_f16_sdwa v25, v144 dst_sel:DWORD dst_unused:UNUSED_PAD src0_sel:WORD_1
	global_store_dwordx4 v[28:29], v[32:35], off
	v_pk_fma_f32 v[20:21], v[20:21], v[96:97], v[24:25]
	s_nop 0
	v_cvt_pk_f16_f32 v24, v20, v21
	v_cvt_f32_f16_e32 v20, v146
	v_cvt_f32_f16_sdwa v21, v146 dst_sel:DWORD dst_unused:UNUSED_PAD src0_sel:WORD_1
	v_pk_fma_f32 v[16:17], v[16:17], v[88:89], v[20:21]
	s_nop 0
	v_cvt_pk_f16_f32 v26, v16, v17
	v_cvt_f32_f16_e32 v16, v145
	v_cvt_f32_f16_sdwa v17, v145 dst_sel:DWORD dst_unused:UNUSED_PAD src0_sel:WORD_1
	v_pk_fma_f32 v[16:17], v[22:23], v[98:99], v[16:17]
	s_nop 0
	v_cvt_pk_f16_f32 v25, v16, v17
	v_cvt_f32_f16_e32 v16, v147
	v_cvt_f32_f16_sdwa v17, v147 dst_sel:DWORD dst_unused:UNUSED_PAD src0_sel:WORD_1
	v_pk_fma_f32 v[16:17], v[18:19], v[90:91], v[16:17]
	s_nop 0
	v_cvt_pk_f16_f32 v27, v16, v17
	v_cvt_f32_f16_e32 v16, v136
	v_cvt_f32_f16_sdwa v17, v136 dst_sel:DWORD dst_unused:UNUSED_PAD src0_sel:WORD_1
	global_store_dwordx4 v[28:29], v[24:27], off offset:256
	v_pk_fma_f32 v[12:13], v[12:13], v[116:117], v[16:17]
	s_nop 0
	v_cvt_pk_f16_f32 v16, v12, v13
	v_cvt_f32_f16_e32 v12, v138
	v_cvt_f32_f16_sdwa v13, v138 dst_sel:DWORD dst_unused:UNUSED_PAD src0_sel:WORD_1
	v_pk_fma_f32 v[8:9], v[8:9], v[108:109], v[12:13]
	s_nop 0
	v_cvt_pk_f16_f32 v18, v8, v9
	v_cvt_f32_f16_e32 v8, v137
	v_cvt_f32_f16_sdwa v9, v137 dst_sel:DWORD dst_unused:UNUSED_PAD src0_sel:WORD_1
	v_pk_fma_f32 v[8:9], v[14:15], v[118:119], v[8:9]
	s_nop 0
	v_cvt_pk_f16_f32 v17, v8, v9
	v_cvt_f32_f16_e32 v8, v139
	v_cvt_f32_f16_sdwa v9, v139 dst_sel:DWORD dst_unused:UNUSED_PAD src0_sel:WORD_1
	v_pk_fma_f32 v[8:9], v[10:11], v[110:111], v[8:9]
	s_nop 0
	v_cvt_pk_f16_f32 v19, v8, v9
	v_lshl_add_u64 v[8:9], s[56:57], 0, v[222:223]
	v_lshl_add_u64 v[12:13], v[8:9], 0, v[220:221]
	v_cvt_f32_f16_e32 v8, v128
	v_cvt_f32_f16_sdwa v9, v128 dst_sel:DWORD dst_unused:UNUSED_PAD src0_sel:WORD_1
	global_store_dwordx4 v[12:13], v[16:19], off
	v_pk_fma_f32 v[4:5], v[4:5], v[96:97], v[8:9]
	s_nop 0
	v_cvt_pk_f16_f32 v8, v4, v5
	v_cvt_f32_f16_e32 v4, v130
	v_cvt_f32_f16_sdwa v5, v130 dst_sel:DWORD dst_unused:UNUSED_PAD src0_sel:WORD_1
	v_pk_fma_f32 v[0:1], v[0:1], v[88:89], v[4:5]
	s_nop 0
	v_cvt_pk_f16_f32 v10, v0, v1
	v_cvt_f32_f16_e32 v0, v129
	v_cvt_f32_f16_sdwa v1, v129 dst_sel:DWORD dst_unused:UNUSED_PAD src0_sel:WORD_1
	v_pk_fma_f32 v[0:1], v[6:7], v[98:99], v[0:1]
	s_nop 0
	v_cvt_pk_f16_f32 v9, v0, v1
	v_cvt_f32_f16_e32 v0, v131
	v_cvt_f32_f16_sdwa v1, v131 dst_sel:DWORD dst_unused:UNUSED_PAD src0_sel:WORD_1
	v_pk_fma_f32 v[0:1], v[2:3], v[90:91], v[0:1]
	s_nop 0
	v_cvt_pk_f16_f32 v11, v0, v1
	global_store_dwordx4 v[12:13], v[8:11], off offset:256
	s_cbranch_vccz .LBB0_1178
	s_waitcnt vmcnt(0)
	s_cmpk_gt_u32 s34, 0xff
	s_cbranch_scc1 .LBB0_1189
	s_barrier
